# static s_setprio 1 for the younger half set once at kernel entry (whole kernel incl. mixers and epilogues), per-segment flips deleted
# baseline (speedup 1.0000x reference)
_Z6mk_fwd4Args:
	v_readfirstlane_b32 s100, v0
	s_and_b32 s100, s100, 0x3ff
	s_cmp_lt_u32 s100, 0x100
	s_cbranch_scc1 .Lsp_old
	s_setprio 1
.Lsp_old:
	s_mov_b64 s[6:7], s[0:1]
	s_load_dword s0, s[0:1], 0xd8
	s_add_u32 s4, s6, 0xd8
	s_addc_u32 s5, s7, 0
	s_mov_b32 s96, s2
	v_writelane_b32 v249, s4, 0
	s_nop 1
	v_writelane_b32 v249, s5, 1
	s_waitcnt lgkmcnt(0)
	v_writelane_b32 v249, s0, 2
	s_and_b32 s0, s0, 7
	s_cmp_lg_u32 s0, 0
	s_mov_b32 s0, s2
	v_writelane_b32 v249, s0, 3
	s_cbranch_scc0 .LBB0_59
	v_cmp_gt_u32_e32 vcc, 32, v0
	s_and_saveexec_b64 s[4:5], vcc

.Lip_nopf:
	s_add_u32 s38, s42, 0x80
	s_addc_u32 s39, s43, 0
	s_add_i32 s60, 0, 0x10000
	s_add_i32 s61, 0, 0x14000
	v_add_u32_e32 v70, s60, v207
	v_add_u32_e32 v110, s61, v207
	ds_read_b128 v[42:45], v70
	ds_read_b128 v[46:49], v70 offset:1024
	ds_read_b128 v[66:69], v70 offset:2048
	ds_read_b128 v[70:73], v70 offset:3072
	ds_read_b128 v[86:89], v110
	ds_read_b128 v[90:93], v110 offset:1024
	ds_read_b128 v[106:109], v110 offset:2048
	ds_read_b128 v[110:113], v110 offset:3072
	s_add_u32 s58, s19, 0x7ff80
	s_addc_u32 s59, s54, 0
	ds_read_b128 v[130:133], v237
	ds_read_b128 v[134:137], v237 offset:1024
	ds_read_b128 v[154:157], v237 offset:2048
	ds_read_b128 v[158:161], v237 offset:3072
	ds_read_b128 v[178:181], v237 offset:4096
	ds_read_b128 v[182:185], v237 offset:5120
	ds_read_b128 v[186:189], v237 offset:6144
	ds_read_b128 v[190:193], v237 offset:7168
	s_add_i32 m0, s46, 0xc000
	v_lshl_add_u64 v[194:195], s[58:59], 0, v[208:209]
	s_add_u32 s58, s58, 0x40000
	s_addc_u32 s59, s59, 0
	global_load_lds_dwordx4 v[194:195], off
	s_add_i32 m0, s46, 0xe000
	v_lshl_add_u64 v[194:195], s[58:59], 0, v[208:209]
	global_load_lds_dwordx4 v[194:195], off
	s_waitcnt vmcnt(8)
	s_waitcnt lgkmcnt(0)
	s_barrier
	s_waitcnt lgkmcnt(0)
	v_mfma_f32_16x16x32_bf16 v[174:177], v[42:45], v[130:133], v[174:177]
	v_mfma_f32_16x16x32_bf16 v[170:173], v[66:69], v[130:133], v[170:173]
	v_mfma_f32_16x16x32_bf16 v[150:153], v[42:45], v[154:157], v[150:153]
	v_mfma_f32_16x16x32_bf16 v[146:149], v[66:69], v[154:157], v[146:149]
	v_mfma_f32_16x16x32_bf16 v[126:129], v[42:45], v[178:181], v[126:129]
	v_mfma_f32_16x16x32_bf16 v[122:125], v[66:69], v[178:181], v[122:125]
	v_mfma_f32_16x16x32_bf16 v[102:105], v[42:45], v[186:189], v[102:105]
	v_mfma_f32_16x16x32_bf16 v[98:101], v[66:69], v[186:189], v[98:101]
	v_mfma_f32_16x16x32_bf16 v[174:177], v[46:49], v[134:137], v[174:177]
	v_mfma_f32_16x16x32_bf16 v[170:173], v[70:73], v[134:137], v[170:173]
	v_mfma_f32_16x16x32_bf16 v[150:153], v[46:49], v[158:161], v[150:153]
	v_mfma_f32_16x16x32_bf16 v[146:149], v[70:73], v[158:161], v[146:149]
	v_mfma_f32_16x16x32_bf16 v[126:129], v[46:49], v[182:185], v[126:129]
	v_mfma_f32_16x16x32_bf16 v[122:125], v[70:73], v[182:185], v[122:125]
	v_mfma_f32_16x16x32_bf16 v[102:105], v[46:49], v[190:193], v[102:105]
	v_mfma_f32_16x16x32_bf16 v[98:101], v[70:73], v[190:193], v[98:101]
	v_mfma_f32_16x16x32_bf16 v[166:169], v[86:89], v[130:133], v[166:169]
	v_mfma_f32_16x16x32_bf16 v[130:133], v[106:109], v[130:133], v[162:165]
	v_mfma_f32_16x16x32_bf16 v[138:141], v[106:109], v[154:157], v[138:141]
	v_mfma_f32_16x16x32_bf16 v[118:121], v[86:89], v[178:181], v[118:121]
	v_mfma_f32_16x16x32_bf16 v[114:117], v[106:109], v[178:181], v[114:117]
	v_mfma_f32_16x16x32_bf16 v[94:97], v[86:89], v[186:189], v[94:97]
	v_mfma_f32_16x16x32_bf16 v[82:85], v[106:109], v[186:189], v[82:85]
	v_mfma_f32_16x16x32_bf16 v[166:169], v[90:93], v[134:137], v[166:169]
	v_mfma_f32_16x16x32_bf16 v[130:133], v[110:113], v[134:137], v[130:133]
	v_mfma_f32_16x16x32_bf16 v[134:137], v[86:89], v[154:157], v[142:145]
	v_mfma_f32_16x16x32_bf16 v[138:141], v[110:113], v[158:161], v[138:141]
	v_mfma_f32_16x16x32_bf16 v[118:121], v[90:93], v[182:185], v[118:121]
	v_mfma_f32_16x16x32_bf16 v[114:117], v[110:113], v[182:185], v[114:117]
	v_mfma_f32_16x16x32_bf16 v[94:97], v[90:93], v[190:193], v[94:97]
	v_mfma_f32_16x16x32_bf16 v[82:85], v[110:113], v[190:193], v[82:85]
	v_mfma_f32_16x16x32_bf16 v[134:137], v[90:93], v[158:161], v[134:137]
	s_barrier
	s_mov_b64 s[58:59], s[40:41]
	ds_read_b128 v[142:145], v237 offset:16384
	ds_read_b128 v[154:157], v237 offset:17408
	ds_read_b128 v[158:161], v237 offset:18432
	ds_read_b128 v[162:165], v237 offset:19456
	ds_read_b128 v[178:181], v237 offset:20480
	ds_read_b128 v[182:185], v237 offset:21504
	ds_read_b128 v[186:189], v237 offset:22528
	ds_read_b128 v[190:193], v237 offset:23552
	s_add_i32 s60, s60, s45
	v_lshl_add_u64 v[194:195], s[58:59], 0, v[202:203]
	s_add_u32 s58, s58, 0x40000
	s_mov_b32 m0, s60
	s_addc_u32 s59, s59, 0
	global_load_lds_dwordx4 v[194:195], off
	s_add_i32 m0, s60, 0x2000
	v_lshl_add_u64 v[194:195], s[58:59], 0, v[202:203]
	s_add_u32 s58, s40, 0x80000
	s_addc_u32 s59, s41, 0
	global_load_lds_dwordx4 v[194:195], off
	s_add_i32 s60, s61, s45
	v_lshl_add_u64 v[194:195], s[58:59], 0, v[202:203]
	s_add_u32 s58, s58, 0x40000
	s_mov_b32 m0, s60
	s_addc_u32 s59, s59, 0
	global_load_lds_dwordx4 v[194:195], off
	s_add_i32 m0, s60, 0x2000
	v_lshl_add_u64 v[194:195], s[58:59], 0, v[202:203]
	s_mov_b64 s[58:59], s[42:43]
	global_load_lds_dwordx4 v[194:195], off
	s_mov_b32 m0, s46
	v_lshl_add_u64 v[194:195], s[58:59], 0, v[208:209]
	s_add_u32 s58, s58, 0x40000
	s_addc_u32 s59, s59, 0
	global_load_lds_dwordx4 v[194:195], off
	s_mov_b32 m0, s47
	v_lshl_add_u64 v[194:195], s[58:59], 0, v[208:209]
	global_load_lds_dwordx4 v[194:195], off
	s_waitcnt vmcnt(8)
	s_waitcnt lgkmcnt(0)
	s_barrier
	s_waitcnt lgkmcnt(0)
	v_mfma_f32_16x16x32_bf16 v[78:81], v[42:45], v[142:145], v[78:81]
	v_mfma_f32_16x16x32_bf16 v[74:77], v[66:69], v[142:145], v[74:77]
	v_mfma_f32_16x16x32_bf16 v[54:57], v[42:45], v[158:161], v[54:57]
	v_mfma_f32_16x16x32_bf16 v[50:53], v[66:69], v[158:161], v[50:53]
	v_mfma_f32_16x16x32_bf16 v[30:33], v[42:45], v[178:181], v[30:33]
	v_mfma_f32_16x16x32_bf16 v[26:29], v[66:69], v[178:181], v[26:29]
	v_mfma_f32_16x16x32_bf16 v[14:17], v[42:45], v[186:189], v[14:17]
	v_mfma_f32_16x16x32_bf16 v[10:13], v[66:69], v[186:189], v[10:13]
	v_mfma_f32_16x16x32_bf16 v[78:81], v[46:49], v[154:157], v[78:81]
	v_mfma_f32_16x16x32_bf16 v[74:77], v[70:73], v[154:157], v[74:77]
	v_mfma_f32_16x16x32_bf16 v[54:57], v[46:49], v[162:165], v[54:57]
	v_mfma_f32_16x16x32_bf16 v[50:53], v[70:73], v[162:165], v[50:53]
	v_mfma_f32_16x16x32_bf16 v[30:33], v[46:49], v[182:185], v[30:33]
	v_mfma_f32_16x16x32_bf16 v[26:29], v[70:73], v[182:185], v[26:29]
	v_mfma_f32_16x16x32_bf16 v[14:17], v[46:49], v[190:193], v[14:17]
	v_mfma_f32_16x16x32_bf16 v[10:13], v[70:73], v[190:193], v[10:13]
	v_mfma_f32_16x16x32_bf16 v[38:41], v[86:89], v[158:161], v[38:41]
	v_mfma_f32_16x16x32_bf16 v[34:37], v[106:109], v[158:161], v[34:37]
	v_mfma_f32_16x16x32_bf16 v[22:25], v[86:89], v[178:181], v[22:25]
	v_mfma_f32_16x16x32_bf16 v[18:21], v[106:109], v[178:181], v[18:21]
	v_mfma_f32_16x16x32_bf16 v[6:9], v[86:89], v[186:189], v[6:9]
	v_mfma_f32_16x16x32_bf16 v[2:5], v[106:109], v[186:189], v[2:5]
	v_mfma_f32_16x16x32_bf16 v[42:45], v[86:89], v[142:145], v[62:65]
	v_mfma_f32_16x16x32_bf16 v[46:49], v[106:109], v[142:145], v[58:61]
	v_mfma_f32_16x16x32_bf16 v[38:41], v[90:93], v[162:165], v[38:41]
	v_mfma_f32_16x16x32_bf16 v[34:37], v[110:113], v[162:165], v[34:37]
	v_mfma_f32_16x16x32_bf16 v[22:25], v[90:93], v[182:185], v[22:25]
	v_mfma_f32_16x16x32_bf16 v[18:21], v[110:113], v[182:185], v[18:21]
	v_mfma_f32_16x16x32_bf16 v[6:9], v[90:93], v[190:193], v[6:9]
	v_mfma_f32_16x16x32_bf16 v[2:5], v[110:113], v[190:193], v[2:5]
	v_mfma_f32_16x16x32_bf16 v[42:45], v[90:93], v[154:157], v[42:45]
	v_mfma_f32_16x16x32_bf16 v[46:49], v[110:113], v[154:157], v[46:49]
	s_barrier
	s_add_i32 s58, 0, 0x18000
	s_add_i32 s59, 0, 0x1c000
	v_add_u32_e32 v70, s58, v207
	v_add_u32_e32 v110, s59, v207
	ds_read_b128 v[58:61], v70
	ds_read_b128 v[62:65], v70 offset:1024
	ds_read_b128 v[66:69], v70 offset:2048
	ds_read_b128 v[70:73], v70 offset:3072
	ds_read_b128 v[86:89], v110
	ds_read_b128 v[90:93], v110 offset:1024
	ds_read_b128 v[106:109], v110 offset:2048
	ds_read_b128 v[110:113], v110 offset:3072
	s_add_u32 s42, s42, 0x80000
	s_addc_u32 s43, s43, 0
	ds_read_b128 v[142:145], v237 offset:32768
	ds_read_b128 v[154:157], v237 offset:33792
	ds_read_b128 v[158:161], v237 offset:34816
	ds_read_b128 v[178:181], v237 offset:35840
	ds_read_b128 v[182:185], v237 offset:36864
	ds_read_b128 v[186:189], v237 offset:37888
	ds_read_b128 v[190:193], v237 offset:38912
	ds_read_b128 v[194:197], v237 offset:39936
	s_mov_b32 m0, s48
	v_lshl_add_u64 v[162:163], s[42:43], 0, v[208:209]
	s_add_u32 s42, s42, 0x40000
	s_addc_u32 s43, s43, 0
	global_load_lds_dwordx4 v[162:163], off
	s_mov_b32 m0, s49
	v_lshl_add_u64 v[162:163], s[42:43], 0, v[208:209]
	global_load_lds_dwordx4 v[162:163], off
	s_waitcnt vmcnt(8)
	s_waitcnt lgkmcnt(0)
	s_barrier
	s_waitcnt lgkmcnt(0)
	v_mfma_f32_16x16x32_bf16 v[162:165], v[58:61], v[142:145], v[174:177]
	v_mfma_f32_16x16x32_bf16 v[174:177], v[62:65], v[154:157], v[162:165]
	v_mfma_f32_16x16x32_bf16 v[162:165], v[66:69], v[142:145], v[170:173]
	v_mfma_f32_16x16x32_bf16 v[150:153], v[58:61], v[158:161], v[150:153]
	v_mfma_f32_16x16x32_bf16 v[146:149], v[66:69], v[158:161], v[146:149]
	v_mfma_f32_16x16x32_bf16 v[126:129], v[58:61], v[182:185], v[126:129]
	v_mfma_f32_16x16x32_bf16 v[122:125], v[66:69], v[182:185], v[122:125]
	v_mfma_f32_16x16x32_bf16 v[102:105], v[58:61], v[190:193], v[102:105]
	v_mfma_f32_16x16x32_bf16 v[98:101], v[66:69], v[190:193], v[98:101]
	v_mfma_f32_16x16x32_bf16 v[170:173], v[70:73], v[154:157], v[162:165]
	v_mfma_f32_16x16x32_bf16 v[150:153], v[62:65], v[178:181], v[150:153]
	v_mfma_f32_16x16x32_bf16 v[146:149], v[70:73], v[178:181], v[146:149]
	v_mfma_f32_16x16x32_bf16 v[126:129], v[62:65], v[186:189], v[126:129]
	v_mfma_f32_16x16x32_bf16 v[122:125], v[70:73], v[186:189], v[122:125]
	v_mfma_f32_16x16x32_bf16 v[102:105], v[62:65], v[194:197], v[102:105]
	v_mfma_f32_16x16x32_bf16 v[98:101], v[70:73], v[194:197], v[98:101]
	v_mfma_f32_16x16x32_bf16 v[162:165], v[86:89], v[142:145], v[166:169]
	v_mfma_f32_16x16x32_bf16 v[130:133], v[106:109], v[142:145], v[130:133]
	v_mfma_f32_16x16x32_bf16 v[166:169], v[90:93], v[154:157], v[162:165]
	v_mfma_f32_16x16x32_bf16 v[162:165], v[110:113], v[154:157], v[130:133]
	v_mfma_f32_16x16x32_bf16 v[130:133], v[86:89], v[158:161], v[134:137]
	v_mfma_f32_16x16x32_bf16 v[142:145], v[90:93], v[178:181], v[130:133]
	v_mfma_f32_16x16x32_bf16 v[130:133], v[106:109], v[158:161], v[138:141]
	v_mfma_f32_16x16x32_bf16 v[118:121], v[86:89], v[182:185], v[118:121]
	v_mfma_f32_16x16x32_bf16 v[114:117], v[106:109], v[182:185], v[114:117]
	v_mfma_f32_16x16x32_bf16 v[94:97], v[86:89], v[190:193], v[94:97]
	v_mfma_f32_16x16x32_bf16 v[82:85], v[106:109], v[190:193], v[82:85]
	v_mfma_f32_16x16x32_bf16 v[138:141], v[110:113], v[178:181], v[130:133]
	v_mfma_f32_16x16x32_bf16 v[118:121], v[90:93], v[186:189], v[118:121]
	v_mfma_f32_16x16x32_bf16 v[114:117], v[110:113], v[186:189], v[114:117]
	v_mfma_f32_16x16x32_bf16 v[94:97], v[90:93], v[194:197], v[94:97]
	v_mfma_f32_16x16x32_bf16 v[82:85], v[110:113], v[194:197], v[82:85]
	s_barrier
	s_add_u32 s42, s40, 0x80
	s_addc_u32 s43, s41, 0
	ds_read_b128 v[130:133], v237 offset:49152
	ds_read_b128 v[134:137], v237 offset:50176
	ds_read_b128 v[154:157], v237 offset:51200
	ds_read_b128 v[158:161], v237 offset:52224
	ds_read_b128 v[178:181], v237 offset:53248
	ds_read_b128 v[182:185], v237 offset:54272
	ds_read_b128 v[186:189], v237 offset:55296
	ds_read_b128 v[190:193], v237 offset:56320
	s_add_i32 s58, s58, s45
	v_lshl_add_u64 v[194:195], s[42:43], 0, v[202:203]
	s_mov_b32 m0, s58
	s_add_u32 s42, s42, 0x40000
	global_load_lds_dwordx4 v[194:195], off
	s_addc_u32 s43, s43, 0
	s_add_i32 m0, s58, 0x2000
	s_add_u32 s40, s40, 0x80080
	s_addc_u32 s41, s41, 0
	v_lshl_add_u64 v[194:195], s[42:43], 0, v[202:203]
	global_load_lds_dwordx4 v[194:195], off
	s_add_i32 s42, s59, s45
	v_lshl_add_u64 v[194:195], s[40:41], 0, v[202:203]
	s_add_u32 s40, s40, 0x40000
	s_mov_b32 m0, s42
	s_addc_u32 s41, s41, 0
	global_load_lds_dwordx4 v[194:195], off
	s_add_i32 m0, s42, 0x2000
	v_lshl_add_u64 v[194:195], s[40:41], 0, v[202:203]
	global_load_lds_dwordx4 v[194:195], off
	s_mov_b32 m0, s50
	v_lshl_add_u64 v[194:195], s[38:39], 0, v[208:209]
	s_add_u32 s38, s38, 0x40000
	s_addc_u32 s39, s39, 0
	global_load_lds_dwordx4 v[194:195], off
	s_mov_b32 m0, s51
	v_lshl_add_u64 v[194:195], s[38:39], 0, v[208:209]
	global_load_lds_dwordx4 v[194:195], off
	s_waitcnt vmcnt(8)
	s_waitcnt lgkmcnt(0)
	s_barrier
	s_waitcnt lgkmcnt(0)
	v_mfma_f32_16x16x32_bf16 v[78:81], v[58:61], v[130:133], v[78:81]
	v_mfma_f32_16x16x32_bf16 v[74:77], v[66:69], v[130:133], v[74:77]
	v_mfma_f32_16x16x32_bf16 v[54:57], v[58:61], v[154:157], v[54:57]
	v_mfma_f32_16x16x32_bf16 v[50:53], v[66:69], v[154:157], v[50:53]
	v_mfma_f32_16x16x32_bf16 v[30:33], v[58:61], v[178:181], v[30:33]
	v_mfma_f32_16x16x32_bf16 v[26:29], v[66:69], v[178:181], v[26:29]
	v_mfma_f32_16x16x32_bf16 v[14:17], v[58:61], v[186:189], v[14:17]
	v_mfma_f32_16x16x32_bf16 v[10:13], v[66:69], v[186:189], v[10:13]
	v_mfma_f32_16x16x32_bf16 v[78:81], v[62:65], v[134:137], v[78:81]
	v_mfma_f32_16x16x32_bf16 v[74:77], v[70:73], v[134:137], v[74:77]
	v_mfma_f32_16x16x32_bf16 v[54:57], v[62:65], v[158:161], v[54:57]
	v_mfma_f32_16x16x32_bf16 v[50:53], v[70:73], v[158:161], v[50:53]
	v_mfma_f32_16x16x32_bf16 v[30:33], v[62:65], v[182:185], v[30:33]
	v_mfma_f32_16x16x32_bf16 v[26:29], v[70:73], v[182:185], v[26:29]
	v_mfma_f32_16x16x32_bf16 v[14:17], v[62:65], v[190:193], v[14:17]
	v_mfma_f32_16x16x32_bf16 v[10:13], v[70:73], v[190:193], v[10:13]
	v_mfma_f32_16x16x32_bf16 v[42:45], v[86:89], v[130:133], v[42:45]
	v_mfma_f32_16x16x32_bf16 v[62:65], v[90:93], v[134:137], v[42:45]
	v_mfma_f32_16x16x32_bf16 v[42:45], v[106:109], v[130:133], v[46:49]
	v_mfma_f32_16x16x32_bf16 v[38:41], v[86:89], v[154:157], v[38:41]
	v_mfma_f32_16x16x32_bf16 v[34:37], v[106:109], v[154:157], v[34:37]
	v_mfma_f32_16x16x32_bf16 v[22:25], v[86:89], v[178:181], v[22:25]
	v_mfma_f32_16x16x32_bf16 v[18:21], v[106:109], v[178:181], v[18:21]
	v_mfma_f32_16x16x32_bf16 v[6:9], v[86:89], v[186:189], v[6:9]
	v_mfma_f32_16x16x32_bf16 v[2:5], v[106:109], v[186:189], v[2:5]
	v_mfma_f32_16x16x32_bf16 v[58:61], v[110:113], v[134:137], v[42:45]
	v_mfma_f32_16x16x32_bf16 v[38:41], v[90:93], v[158:161], v[38:41]
	v_mfma_f32_16x16x32_bf16 v[34:37], v[110:113], v[158:161], v[34:37]
	v_mfma_f32_16x16x32_bf16 v[22:25], v[90:93], v[182:185], v[22:25]
	v_mfma_f32_16x16x32_bf16 v[18:21], v[110:113], v[182:185], v[18:21]
	v_mfma_f32_16x16x32_bf16 v[6:9], v[90:93], v[190:193], v[6:9]
	v_mfma_f32_16x16x32_bf16 v[2:5], v[110:113], v[190:193], v[2:5]
	s_barrier
	s_add_i32 s57, s57, 2
	s_add_u32 s19, s19, 0x100
	s_addc_u32 s54, s54, 0
	s_add_u32 s55, s55, 0x100
	s_addc_u32 s56, s56, 0
	s_cmp_gt_u32 s57, 29
	s_cbranch_scc0 .LBB0_293
	s_and_b64 vcc, exec, s[16:17]
	s_cbranch_vccz .LBB0_296
	s_barrier

.LBB0_1013:
	s_add_i32 s78, s10, 2
	s_cmp_eq_u32 s71, s10
	s_cselect_b32 s46, s4, s28
	s_cselect_b32 s47, s5, s29
	s_cselect_b32 s44, s42, s76
	s_cselect_b32 s45, s43, s77
	s_add_u32 s10, s46, 0x80
	s_addc_u32 s11, s47, 0
	s_add_i32 s79, 0, 0x10000
	s_add_i32 s82, 0, 0x14000
	v_add_u32_e32 v142, s79, v179
	v_add_u32_e32 v160, s82, v179
	ds_read_b128 v[130:133], v142
	ds_read_b128 v[134:137], v142 offset:1024
	ds_read_b128 v[138:141], v142 offset:2048
	ds_read_b128 v[142:145], v142 offset:3072
	ds_read_b128 v[146:149], v160
	ds_read_b128 v[150:153], v160 offset:1024
	ds_read_b128 v[154:157], v160 offset:2048
	ds_read_b128 v[160:163], v160 offset:3072
	s_add_u32 s80, s28, 0x7ff80
	v_add_u32_e32 v240, 0, v178
	s_addc_u32 s81, s29, 0
	ds_read_b128 v[164:167], v240
	ds_read_b128 v[168:171], v240 offset:1024
	ds_read_b128 v[172:175], v240 offset:2048
	ds_read_b128 v[212:215], v240 offset:3072
	ds_read_b128 v[216:219], v240 offset:4096
	ds_read_b128 v[220:223], v240 offset:5120
	ds_read_b128 v[224:227], v240 offset:6144
	ds_read_b128 v[236:239], v240 offset:7168
	s_add_i32 m0, s49, 0xc000
	v_lshl_add_u64 v[176:177], s[80:81], 0, v[158:159]
	s_add_u32 s80, s80, 0x40000
	s_addc_u32 s81, s81, 0
	global_load_lds_dwordx4 v[176:177], off
	s_add_i32 m0, s49, 0xe000
	v_lshl_add_u64 v[176:177], s[80:81], 0, v[158:159]
	global_load_lds_dwordx4 v[176:177], off
	s_waitcnt vmcnt(8)
	s_waitcnt lgkmcnt(0)
	s_barrier
	s_waitcnt lgkmcnt(0)
	v_mfma_f32_16x16x32_bf16 v[126:129], v[130:133], v[164:167], v[126:129]
	v_mfma_f32_16x16x32_bf16 v[122:125], v[138:141], v[164:167], v[122:125]
	v_mfma_f32_16x16x32_bf16 v[114:117], v[130:133], v[172:175], v[114:117]
	v_mfma_f32_16x16x32_bf16 v[106:109], v[138:141], v[172:175], v[106:109]
	v_mfma_f32_16x16x32_bf16 v[98:101], v[130:133], v[216:219], v[98:101]
	v_mfma_f32_16x16x32_bf16 v[90:93], v[138:141], v[216:219], v[90:93]
	v_mfma_f32_16x16x32_bf16 v[82:85], v[130:133], v[224:227], v[82:85]
	v_mfma_f32_16x16x32_bf16 v[74:77], v[138:141], v[224:227], v[74:77]
	v_mfma_f32_16x16x32_bf16 v[126:129], v[134:137], v[168:171], v[126:129]
	v_mfma_f32_16x16x32_bf16 v[122:125], v[142:145], v[168:171], v[122:125]
	v_mfma_f32_16x16x32_bf16 v[114:117], v[134:137], v[212:215], v[114:117]
	v_mfma_f32_16x16x32_bf16 v[106:109], v[142:145], v[212:215], v[106:109]
	v_mfma_f32_16x16x32_bf16 v[98:101], v[134:137], v[220:223], v[98:101]
	v_mfma_f32_16x16x32_bf16 v[90:93], v[142:145], v[220:223], v[90:93]
	v_mfma_f32_16x16x32_bf16 v[82:85], v[134:137], v[236:239], v[82:85]
	v_mfma_f32_16x16x32_bf16 v[74:77], v[142:145], v[236:239], v[74:77]
	v_mfma_f32_16x16x32_bf16 v[118:121], v[146:149], v[164:167], v[118:121]
	v_mfma_f32_16x16x32_bf16 v[110:113], v[154:157], v[164:167], v[110:113]
	v_mfma_f32_16x16x32_bf16 v[102:105], v[146:149], v[172:175], v[102:105]
	v_mfma_f32_16x16x32_bf16 v[94:97], v[154:157], v[172:175], v[94:97]
	v_mfma_f32_16x16x32_bf16 v[86:89], v[146:149], v[216:219], v[86:89]
	v_mfma_f32_16x16x32_bf16 v[78:81], v[154:157], v[216:219], v[78:81]
	v_mfma_f32_16x16x32_bf16 v[70:73], v[146:149], v[224:227], v[70:73]
	v_mfma_f32_16x16x32_bf16 v[66:69], v[154:157], v[224:227], v[66:69]
	v_mfma_f32_16x16x32_bf16 v[118:121], v[150:153], v[168:171], v[118:121]
	v_mfma_f32_16x16x32_bf16 v[110:113], v[160:163], v[168:171], v[110:113]
	v_mfma_f32_16x16x32_bf16 v[102:105], v[150:153], v[212:215], v[102:105]
	v_mfma_f32_16x16x32_bf16 v[94:97], v[160:163], v[212:215], v[94:97]
	v_mfma_f32_16x16x32_bf16 v[86:89], v[150:153], v[220:223], v[86:89]
	v_mfma_f32_16x16x32_bf16 v[78:81], v[160:163], v[220:223], v[78:81]
	v_mfma_f32_16x16x32_bf16 v[70:73], v[150:153], v[236:239], v[70:73]
	v_mfma_f32_16x16x32_bf16 v[66:69], v[160:163], v[236:239], v[66:69]
	s_barrier
	s_mov_b64 s[80:81], s[44:45]
	ds_read_b128 v[164:167], v240 offset:16384
	ds_read_b128 v[168:171], v240 offset:17408
	ds_read_b128 v[172:175], v240 offset:18432
	ds_read_b128 v[212:215], v240 offset:19456
	ds_read_b128 v[216:219], v240 offset:20480
	ds_read_b128 v[220:223], v240 offset:21504
	ds_read_b128 v[224:227], v240 offset:22528
	ds_read_b128 v[236:239], v240 offset:23552
	s_add_i32 s79, s79, s48
	v_lshl_add_u64 v[176:177], s[80:81], 0, v[202:203]
	s_add_u32 s80, s80, 0x30000
	s_mov_b32 m0, s79
	s_addc_u32 s81, s81, 0
	global_load_lds_dwordx4 v[176:177], off
	s_add_i32 m0, s79, 0x2000
	v_lshl_add_u64 v[176:177], s[80:81], 0, v[202:203]
	s_add_u32 s80, s44, 0x60000
	s_addc_u32 s81, s45, 0
	global_load_lds_dwordx4 v[176:177], off
	s_add_i32 s79, s82, s48
	v_lshl_add_u64 v[176:177], s[80:81], 0, v[202:203]
	s_add_u32 s80, s80, 0x30000
	s_mov_b32 m0, s79
	s_addc_u32 s81, s81, 0
	global_load_lds_dwordx4 v[176:177], off
	s_add_i32 m0, s79, 0x2000
	v_lshl_add_u64 v[176:177], s[80:81], 0, v[202:203]
	s_mov_b64 s[80:81], s[46:47]
	global_load_lds_dwordx4 v[176:177], off
	s_mov_b32 m0, s49
	v_lshl_add_u64 v[176:177], s[80:81], 0, v[158:159]
	s_add_u32 s80, s80, 0x40000
	s_addc_u32 s81, s81, 0
	global_load_lds_dwordx4 v[176:177], off
	s_mov_b32 m0, s50
	v_lshl_add_u64 v[176:177], s[80:81], 0, v[158:159]
	global_load_lds_dwordx4 v[176:177], off
	s_waitcnt vmcnt(8)
	s_waitcnt lgkmcnt(0)
	s_barrier
	s_waitcnt lgkmcnt(0)
	v_mfma_f32_16x16x32_bf16 v[62:65], v[130:133], v[164:167], v[62:65]
	v_mfma_f32_16x16x32_bf16 v[58:61], v[138:141], v[164:167], v[58:61]
	v_mfma_f32_16x16x32_bf16 v[50:53], v[130:133], v[172:175], v[50:53]
	v_mfma_f32_16x16x32_bf16 v[42:45], v[138:141], v[172:175], v[42:45]
	v_mfma_f32_16x16x32_bf16 v[34:37], v[130:133], v[216:219], v[34:37]
	v_mfma_f32_16x16x32_bf16 v[26:29], v[138:141], v[216:219], v[26:29]
	v_mfma_f32_16x16x32_bf16 v[18:21], v[130:133], v[224:227], v[18:21]
	v_mfma_f32_16x16x32_bf16 v[10:13], v[138:141], v[224:227], v[10:13]
	v_mfma_f32_16x16x32_bf16 v[62:65], v[134:137], v[168:171], v[62:65]
	v_mfma_f32_16x16x32_bf16 v[58:61], v[142:145], v[168:171], v[58:61]
	v_mfma_f32_16x16x32_bf16 v[50:53], v[134:137], v[212:215], v[50:53]
	v_mfma_f32_16x16x32_bf16 v[42:45], v[142:145], v[212:215], v[42:45]
	v_mfma_f32_16x16x32_bf16 v[34:37], v[134:137], v[220:223], v[34:37]
	v_mfma_f32_16x16x32_bf16 v[26:29], v[142:145], v[220:223], v[26:29]
	v_mfma_f32_16x16x32_bf16 v[18:21], v[134:137], v[236:239], v[18:21]
	v_mfma_f32_16x16x32_bf16 v[10:13], v[142:145], v[236:239], v[10:13]
	v_mfma_f32_16x16x32_bf16 v[54:57], v[146:149], v[164:167], v[54:57]
	v_mfma_f32_16x16x32_bf16 v[46:49], v[154:157], v[164:167], v[46:49]
	v_mfma_f32_16x16x32_bf16 v[38:41], v[146:149], v[172:175], v[38:41]
	v_mfma_f32_16x16x32_bf16 v[30:33], v[154:157], v[172:175], v[30:33]
	v_mfma_f32_16x16x32_bf16 v[22:25], v[146:149], v[216:219], v[22:25]
	v_mfma_f32_16x16x32_bf16 v[14:17], v[154:157], v[216:219], v[14:17]
	v_mfma_f32_16x16x32_bf16 v[6:9], v[146:149], v[224:227], v[6:9]
	v_mfma_f32_16x16x32_bf16 v[2:5], v[154:157], v[224:227], v[2:5]
	v_mfma_f32_16x16x32_bf16 v[54:57], v[150:153], v[168:171], v[54:57]
	v_mfma_f32_16x16x32_bf16 v[46:49], v[160:163], v[168:171], v[46:49]
	v_mfma_f32_16x16x32_bf16 v[38:41], v[150:153], v[212:215], v[38:41]
	v_mfma_f32_16x16x32_bf16 v[30:33], v[160:163], v[212:215], v[30:33]
	v_mfma_f32_16x16x32_bf16 v[22:25], v[150:153], v[220:223], v[22:25]
	v_mfma_f32_16x16x32_bf16 v[14:17], v[160:163], v[220:223], v[14:17]
	v_mfma_f32_16x16x32_bf16 v[6:9], v[150:153], v[236:239], v[6:9]
	v_mfma_f32_16x16x32_bf16 v[2:5], v[160:163], v[236:239], v[2:5]
	s_barrier
	s_add_i32 s79, 0, 0x18000
	s_add_i32 s80, 0, 0x1c000
	v_add_u32_e32 v142, s79, v179
	v_add_u32_e32 v160, s80, v179
	ds_read_b128 v[130:133], v142
	ds_read_b128 v[134:137], v142 offset:1024
	ds_read_b128 v[138:141], v142 offset:2048
	ds_read_b128 v[142:145], v142 offset:3072
	ds_read_b128 v[146:149], v160
	ds_read_b128 v[150:153], v160 offset:1024
	ds_read_b128 v[154:157], v160 offset:2048
	ds_read_b128 v[160:163], v160 offset:3072
	s_add_u32 s46, s46, 0x80000
	s_addc_u32 s47, s47, 0
	ds_read_b128 v[164:167], v240 offset:32768
	ds_read_b128 v[168:171], v240 offset:33792
	ds_read_b128 v[172:175], v240 offset:34816
	ds_read_b128 v[212:215], v240 offset:35840
	ds_read_b128 v[216:219], v240 offset:36864
	ds_read_b128 v[220:223], v240 offset:37888
	ds_read_b128 v[224:227], v240 offset:38912
	ds_read_b128 v[236:239], v240 offset:39936
	s_mov_b32 m0, s51
	v_lshl_add_u64 v[176:177], s[46:47], 0, v[158:159]
	s_add_u32 s46, s46, 0x40000
	s_addc_u32 s47, s47, 0
	global_load_lds_dwordx4 v[176:177], off
	s_mov_b32 m0, s52
	v_lshl_add_u64 v[176:177], s[46:47], 0, v[158:159]
	global_load_lds_dwordx4 v[176:177], off
	s_waitcnt vmcnt(8)
	s_waitcnt lgkmcnt(0)
	s_barrier
	s_waitcnt lgkmcnt(0)
	v_mfma_f32_16x16x32_bf16 v[126:129], v[130:133], v[164:167], v[126:129]
	v_mfma_f32_16x16x32_bf16 v[122:125], v[138:141], v[164:167], v[122:125]
	v_mfma_f32_16x16x32_bf16 v[114:117], v[130:133], v[172:175], v[114:117]
	v_mfma_f32_16x16x32_bf16 v[106:109], v[138:141], v[172:175], v[106:109]
	v_mfma_f32_16x16x32_bf16 v[98:101], v[130:133], v[216:219], v[98:101]
	v_mfma_f32_16x16x32_bf16 v[90:93], v[138:141], v[216:219], v[90:93]
	v_mfma_f32_16x16x32_bf16 v[82:85], v[130:133], v[224:227], v[82:85]
	v_mfma_f32_16x16x32_bf16 v[74:77], v[138:141], v[224:227], v[74:77]
	v_mfma_f32_16x16x32_bf16 v[126:129], v[134:137], v[168:171], v[126:129]
	v_mfma_f32_16x16x32_bf16 v[122:125], v[142:145], v[168:171], v[122:125]
	v_mfma_f32_16x16x32_bf16 v[114:117], v[134:137], v[212:215], v[114:117]
	v_mfma_f32_16x16x32_bf16 v[106:109], v[142:145], v[212:215], v[106:109]
	v_mfma_f32_16x16x32_bf16 v[98:101], v[134:137], v[220:223], v[98:101]
	v_mfma_f32_16x16x32_bf16 v[90:93], v[142:145], v[220:223], v[90:93]
	v_mfma_f32_16x16x32_bf16 v[82:85], v[134:137], v[236:239], v[82:85]
	v_mfma_f32_16x16x32_bf16 v[74:77], v[142:145], v[236:239], v[74:77]
	v_mfma_f32_16x16x32_bf16 v[118:121], v[146:149], v[164:167], v[118:121]
	v_mfma_f32_16x16x32_bf16 v[110:113], v[154:157], v[164:167], v[110:113]
	v_mfma_f32_16x16x32_bf16 v[102:105], v[146:149], v[172:175], v[102:105]
	v_mfma_f32_16x16x32_bf16 v[94:97], v[154:157], v[172:175], v[94:97]
	v_mfma_f32_16x16x32_bf16 v[86:89], v[146:149], v[216:219], v[86:89]
	v_mfma_f32_16x16x32_bf16 v[78:81], v[154:157], v[216:219], v[78:81]
	v_mfma_f32_16x16x32_bf16 v[70:73], v[146:149], v[224:227], v[70:73]
	v_mfma_f32_16x16x32_bf16 v[66:69], v[154:157], v[224:227], v[66:69]
	v_mfma_f32_16x16x32_bf16 v[118:121], v[150:153], v[168:171], v[118:121]
	v_mfma_f32_16x16x32_bf16 v[110:113], v[160:163], v[168:171], v[110:113]
	v_mfma_f32_16x16x32_bf16 v[102:105], v[150:153], v[212:215], v[102:105]
	v_mfma_f32_16x16x32_bf16 v[94:97], v[160:163], v[212:215], v[94:97]
	v_mfma_f32_16x16x32_bf16 v[86:89], v[150:153], v[220:223], v[86:89]
	v_mfma_f32_16x16x32_bf16 v[78:81], v[160:163], v[220:223], v[78:81]
	v_mfma_f32_16x16x32_bf16 v[70:73], v[150:153], v[236:239], v[70:73]
	v_mfma_f32_16x16x32_bf16 v[66:69], v[160:163], v[236:239], v[66:69]
	s_barrier
	s_add_u32 s46, s44, 0x80
	s_addc_u32 s47, s45, 0
	ds_read_b128 v[164:167], v240 offset:49152
	ds_read_b128 v[168:171], v240 offset:50176
	ds_read_b128 v[172:175], v240 offset:51200
	ds_read_b128 v[212:215], v240 offset:52224
	ds_read_b128 v[216:219], v240 offset:53248
	ds_read_b128 v[220:223], v240 offset:54272
	ds_read_b128 v[224:227], v240 offset:55296
	ds_read_b128 v[236:239], v240 offset:56320
	s_add_i32 s79, s79, s48
	v_lshl_add_u64 v[176:177], s[46:47], 0, v[202:203]
	s_mov_b32 m0, s79
	s_add_u32 s46, s46, 0x30000
	global_load_lds_dwordx4 v[176:177], off
	s_addc_u32 s47, s47, 0
	s_add_i32 m0, s79, 0x2000
	s_add_u32 s44, s44, 0x60080
	s_addc_u32 s45, s45, 0
	v_lshl_add_u64 v[176:177], s[46:47], 0, v[202:203]
	global_load_lds_dwordx4 v[176:177], off
	s_add_i32 s46, s80, s48
	v_lshl_add_u64 v[176:177], s[44:45], 0, v[202:203]
	s_add_u32 s44, s44, 0x30000
	s_mov_b32 m0, s46
	s_addc_u32 s45, s45, 0
	global_load_lds_dwordx4 v[176:177], off
	s_add_i32 m0, s46, 0x2000
	v_lshl_add_u64 v[176:177], s[44:45], 0, v[202:203]
	global_load_lds_dwordx4 v[176:177], off
	s_mov_b32 m0, s53
	v_lshl_add_u64 v[176:177], s[10:11], 0, v[158:159]
	s_add_u32 s10, s10, 0x40000
	s_addc_u32 s11, s11, 0
	global_load_lds_dwordx4 v[176:177], off
	s_mov_b32 m0, s54
	v_lshl_add_u64 v[176:177], s[10:11], 0, v[158:159]
	global_load_lds_dwordx4 v[176:177], off
	s_waitcnt vmcnt(8)
	s_waitcnt lgkmcnt(0)
	s_barrier
	s_waitcnt lgkmcnt(0)
	v_mfma_f32_16x16x32_bf16 v[62:65], v[130:133], v[164:167], v[62:65]
	v_mfma_f32_16x16x32_bf16 v[58:61], v[138:141], v[164:167], v[58:61]
	v_mfma_f32_16x16x32_bf16 v[50:53], v[130:133], v[172:175], v[50:53]
	v_mfma_f32_16x16x32_bf16 v[42:45], v[138:141], v[172:175], v[42:45]
	v_mfma_f32_16x16x32_bf16 v[34:37], v[130:133], v[216:219], v[34:37]
	v_mfma_f32_16x16x32_bf16 v[26:29], v[138:141], v[216:219], v[26:29]
	v_mfma_f32_16x16x32_bf16 v[18:21], v[130:133], v[224:227], v[18:21]
	v_mfma_f32_16x16x32_bf16 v[10:13], v[138:141], v[224:227], v[10:13]
	v_mfma_f32_16x16x32_bf16 v[62:65], v[134:137], v[168:171], v[62:65]
	v_mfma_f32_16x16x32_bf16 v[58:61], v[142:145], v[168:171], v[58:61]
	v_mfma_f32_16x16x32_bf16 v[50:53], v[134:137], v[212:215], v[50:53]
	v_mfma_f32_16x16x32_bf16 v[42:45], v[142:145], v[212:215], v[42:45]
	v_mfma_f32_16x16x32_bf16 v[34:37], v[134:137], v[220:223], v[34:37]
	v_mfma_f32_16x16x32_bf16 v[26:29], v[142:145], v[220:223], v[26:29]
	v_mfma_f32_16x16x32_bf16 v[18:21], v[134:137], v[236:239], v[18:21]
	v_mfma_f32_16x16x32_bf16 v[10:13], v[142:145], v[236:239], v[10:13]
	v_mfma_f32_16x16x32_bf16 v[54:57], v[146:149], v[164:167], v[54:57]
	v_mfma_f32_16x16x32_bf16 v[46:49], v[154:157], v[164:167], v[46:49]
	v_mfma_f32_16x16x32_bf16 v[38:41], v[146:149], v[172:175], v[38:41]
	v_mfma_f32_16x16x32_bf16 v[30:33], v[154:157], v[172:175], v[30:33]
	v_mfma_f32_16x16x32_bf16 v[22:25], v[146:149], v[216:219], v[22:25]
	v_mfma_f32_16x16x32_bf16 v[14:17], v[154:157], v[216:219], v[14:17]
	v_mfma_f32_16x16x32_bf16 v[6:9], v[146:149], v[224:227], v[6:9]
	v_mfma_f32_16x16x32_bf16 v[2:5], v[154:157], v[224:227], v[2:5]
	v_mfma_f32_16x16x32_bf16 v[54:57], v[150:153], v[168:171], v[54:57]
	v_mfma_f32_16x16x32_bf16 v[46:49], v[160:163], v[168:171], v[46:49]
	v_mfma_f32_16x16x32_bf16 v[38:41], v[150:153], v[212:215], v[38:41]
	v_mfma_f32_16x16x32_bf16 v[30:33], v[160:163], v[212:215], v[30:33]
	v_mfma_f32_16x16x32_bf16 v[22:25], v[150:153], v[220:223], v[22:25]
	v_mfma_f32_16x16x32_bf16 v[14:17], v[160:163], v[220:223], v[14:17]
	v_mfma_f32_16x16x32_bf16 v[6:9], v[150:153], v[236:239], v[6:9]
	v_mfma_f32_16x16x32_bf16 v[2:5], v[160:163], v[236:239], v[2:5]
	s_barrier
	s_add_u32 s28, s28, 0x100
	s_addc_u32 s29, s29, 0
	s_add_u32 s76, s76, 0x100
	s_addc_u32 s77, s77, 0
	s_cmp_ge_i32 s78, s69
	s_mov_b32 s10, s78
	s_cbranch_scc0 .LBB0_1013
	s_and_b64 vcc, exec, s[18:19]
	s_cbranch_vccz .LBB0_1016
	s_barrier

.Lg0_nopf:
	s_add_u32 s10, s46, 0x80
	s_addc_u32 s11, s47, 0
	s_add_i32 s29, 0, 0x10000
	s_add_i32 s78, 0, 0x14000
	v_add_u32_e32 v142, s29, v179
	v_add_u32_e32 v160, s78, v179
	ds_read_b128 v[130:133], v142
	ds_read_b128 v[134:137], v142 offset:1024
	ds_read_b128 v[138:141], v142 offset:2048
	ds_read_b128 v[142:145], v142 offset:3072
	ds_read_b128 v[146:149], v160
	ds_read_b128 v[150:153], v160 offset:1024
	ds_read_b128 v[154:157], v160 offset:2048
	ds_read_b128 v[160:163], v160 offset:3072
	s_add_u32 s76, s74, 0x7ff80
	v_add_u32_e32 v200, 0, v178
	s_addc_u32 s77, s75, 0
	ds_read_b128 v[164:167], v200
	ds_read_b128 v[168:171], v200 offset:1024
	ds_read_b128 v[172:175], v200 offset:2048
	ds_read_b128 v[180:183], v200 offset:3072
	ds_read_b128 v[184:187], v200 offset:4096
	ds_read_b128 v[188:191], v200 offset:5120
	ds_read_b128 v[192:195], v200 offset:6144
	ds_read_b128 v[196:199], v200 offset:7168
	s_add_i32 m0, s49, 0xc000
	v_lshl_add_u64 v[176:177], s[76:77], 0, v[158:159]
	s_add_u32 s76, s76, 0x40000
	s_addc_u32 s77, s77, 0
	global_load_lds_dwordx4 v[176:177], off
	s_add_i32 m0, s49, 0xe000
	v_lshl_add_u64 v[176:177], s[76:77], 0, v[158:159]
	global_load_lds_dwordx4 v[176:177], off
	s_waitcnt vmcnt(8)
	s_waitcnt lgkmcnt(0)
	s_barrier
	s_waitcnt lgkmcnt(0)
	v_mfma_i32_16x16x64_i8 v[126:129], v[130:133], v[164:167], v[126:129]
	v_mfma_i32_16x16x64_i8 v[122:125], v[138:141], v[164:167], v[122:125]
	v_mfma_i32_16x16x64_i8 v[118:121], v[130:133], v[172:175], v[118:121]
	v_mfma_i32_16x16x64_i8 v[114:117], v[138:141], v[172:175], v[114:117]
	v_mfma_i32_16x16x64_i8 v[102:105], v[130:133], v[184:187], v[102:105]
	v_mfma_i32_16x16x64_i8 v[98:101], v[138:141], v[184:187], v[98:101]
	v_mfma_i32_16x16x64_i8 v[86:89], v[130:133], v[192:195], v[86:89]
	v_mfma_i32_16x16x64_i8 v[82:85], v[138:141], v[192:195], v[82:85]
	v_mfma_i32_16x16x64_i8 v[126:129], v[134:137], v[168:171], v[126:129]
	v_mfma_i32_16x16x64_i8 v[122:125], v[142:145], v[168:171], v[122:125]
	v_mfma_i32_16x16x64_i8 v[118:121], v[134:137], v[180:183], v[118:121]
	v_mfma_i32_16x16x64_i8 v[114:117], v[142:145], v[180:183], v[114:117]
	v_mfma_i32_16x16x64_i8 v[102:105], v[134:137], v[188:191], v[102:105]
	v_mfma_i32_16x16x64_i8 v[98:101], v[142:145], v[188:191], v[98:101]
	v_mfma_i32_16x16x64_i8 v[86:89], v[134:137], v[196:199], v[86:89]
	v_mfma_i32_16x16x64_i8 v[82:85], v[142:145], v[196:199], v[82:85]
	v_mfma_i32_16x16x64_i8 v[110:113], v[146:149], v[164:167], v[110:113]
	v_mfma_i32_16x16x64_i8 v[106:109], v[154:157], v[164:167], v[106:109]
	v_mfma_i32_16x16x64_i8 v[94:97], v[146:149], v[172:175], v[94:97]
	v_mfma_i32_16x16x64_i8 v[90:93], v[154:157], v[172:175], v[90:93]
	v_mfma_i32_16x16x64_i8 v[78:81], v[146:149], v[184:187], v[78:81]
	v_mfma_i32_16x16x64_i8 v[74:77], v[154:157], v[184:187], v[74:77]
	v_mfma_i32_16x16x64_i8 v[70:73], v[146:149], v[192:195], v[70:73]
	v_mfma_i32_16x16x64_i8 v[66:69], v[154:157], v[192:195], v[66:69]
	v_mfma_i32_16x16x64_i8 v[110:113], v[150:153], v[168:171], v[110:113]
	v_mfma_i32_16x16x64_i8 v[106:109], v[160:163], v[168:171], v[106:109]
	v_mfma_i32_16x16x64_i8 v[94:97], v[150:153], v[180:183], v[94:97]
	v_mfma_i32_16x16x64_i8 v[90:93], v[160:163], v[180:183], v[90:93]
	v_mfma_i32_16x16x64_i8 v[78:81], v[150:153], v[188:191], v[78:81]
	v_mfma_i32_16x16x64_i8 v[74:77], v[160:163], v[188:191], v[74:77]
	v_mfma_i32_16x16x64_i8 v[70:73], v[150:153], v[196:199], v[70:73]
	v_mfma_i32_16x16x64_i8 v[66:69], v[160:163], v[196:199], v[66:69]
	s_barrier
	s_mov_b64 s[76:77], s[44:45]
	ds_read_b128 v[164:167], v200 offset:16384
	ds_read_b128 v[168:171], v200 offset:17408
	ds_read_b128 v[172:175], v200 offset:18432
	ds_read_b128 v[180:183], v200 offset:19456
	ds_read_b128 v[184:187], v200 offset:20480
	ds_read_b128 v[188:191], v200 offset:21504
	ds_read_b128 v[192:195], v200 offset:22528
	ds_read_b128 v[196:199], v200 offset:23552
	s_add_i32 s29, s29, s48
	v_lshl_add_u64 v[176:177], s[76:77], 0, v[202:203]
	s_add_u32 s76, s76, 0x30000
	s_mov_b32 m0, s29
	s_addc_u32 s77, s77, 0
	global_load_lds_dwordx4 v[176:177], off
	s_add_i32 m0, s29, 0x2000
	v_lshl_add_u64 v[176:177], s[76:77], 0, v[202:203]
	s_add_u32 s76, s44, 0x60000
	s_addc_u32 s77, s45, 0
	global_load_lds_dwordx4 v[176:177], off
	s_add_i32 s29, s78, s48
	v_lshl_add_u64 v[176:177], s[76:77], 0, v[202:203]
	s_add_u32 s76, s76, 0x30000
	s_mov_b32 m0, s29
	s_addc_u32 s77, s77, 0
	global_load_lds_dwordx4 v[176:177], off
	s_add_i32 m0, s29, 0x2000
	v_lshl_add_u64 v[176:177], s[76:77], 0, v[202:203]
	s_mov_b64 s[76:77], s[46:47]
	global_load_lds_dwordx4 v[176:177], off
	s_mov_b32 m0, s49
	v_lshl_add_u64 v[176:177], s[76:77], 0, v[158:159]
	s_add_u32 s76, s76, 0x40000
	s_addc_u32 s77, s77, 0
	global_load_lds_dwordx4 v[176:177], off
	s_mov_b32 m0, s50
	v_lshl_add_u64 v[176:177], s[76:77], 0, v[158:159]
	global_load_lds_dwordx4 v[176:177], off
	s_waitcnt vmcnt(8)
	s_waitcnt lgkmcnt(0)
	s_barrier
	s_waitcnt lgkmcnt(0)
	v_mfma_i32_16x16x64_i8 v[62:65], v[130:133], v[164:167], v[62:65]
	v_mfma_i32_16x16x64_i8 v[58:61], v[138:141], v[164:167], v[58:61]
	v_mfma_i32_16x16x64_i8 v[54:57], v[130:133], v[172:175], v[54:57]
	v_mfma_i32_16x16x64_i8 v[50:53], v[138:141], v[172:175], v[50:53]
	v_mfma_i32_16x16x64_i8 v[38:41], v[130:133], v[184:187], v[38:41]
	v_mfma_i32_16x16x64_i8 v[34:37], v[138:141], v[184:187], v[34:37]
	v_mfma_i32_16x16x64_i8 v[14:17], v[130:133], v[192:195], v[14:17]
	v_mfma_i32_16x16x64_i8 v[10:13], v[138:141], v[192:195], v[10:13]
	v_mfma_i32_16x16x64_i8 v[62:65], v[134:137], v[168:171], v[62:65]
	v_mfma_i32_16x16x64_i8 v[58:61], v[142:145], v[168:171], v[58:61]
	v_mfma_i32_16x16x64_i8 v[54:57], v[134:137], v[180:183], v[54:57]
	v_mfma_i32_16x16x64_i8 v[50:53], v[142:145], v[180:183], v[50:53]
	v_mfma_i32_16x16x64_i8 v[38:41], v[134:137], v[188:191], v[38:41]
	v_mfma_i32_16x16x64_i8 v[34:37], v[142:145], v[188:191], v[34:37]
	v_mfma_i32_16x16x64_i8 v[14:17], v[134:137], v[196:199], v[14:17]
	v_mfma_i32_16x16x64_i8 v[10:13], v[142:145], v[196:199], v[10:13]
	v_mfma_i32_16x16x64_i8 v[46:49], v[146:149], v[164:167], v[46:49]
	v_mfma_i32_16x16x64_i8 v[42:45], v[154:157], v[164:167], v[42:45]
	v_mfma_i32_16x16x64_i8 v[30:33], v[146:149], v[172:175], v[30:33]
	v_mfma_i32_16x16x64_i8 v[26:29], v[154:157], v[172:175], v[26:29]
	v_mfma_i32_16x16x64_i8 v[22:25], v[146:149], v[184:187], v[22:25]
	v_mfma_i32_16x16x64_i8 v[18:21], v[154:157], v[184:187], v[18:21]
	v_mfma_i32_16x16x64_i8 v[6:9], v[146:149], v[192:195], v[6:9]
	v_mfma_i32_16x16x64_i8 v[2:5], v[154:157], v[192:195], v[2:5]
	v_mfma_i32_16x16x64_i8 v[46:49], v[150:153], v[168:171], v[46:49]
	v_mfma_i32_16x16x64_i8 v[42:45], v[160:163], v[168:171], v[42:45]
	v_mfma_i32_16x16x64_i8 v[30:33], v[150:153], v[180:183], v[30:33]
	v_mfma_i32_16x16x64_i8 v[26:29], v[160:163], v[180:183], v[26:29]
	v_mfma_i32_16x16x64_i8 v[22:25], v[150:153], v[188:191], v[22:25]
	v_mfma_i32_16x16x64_i8 v[18:21], v[160:163], v[188:191], v[18:21]
	v_mfma_i32_16x16x64_i8 v[6:9], v[150:153], v[196:199], v[6:9]
	v_mfma_i32_16x16x64_i8 v[2:5], v[160:163], v[196:199], v[2:5]
	s_barrier
	s_add_i32 s29, 0, 0x18000
	s_add_i32 s76, 0, 0x1c000
	v_add_u32_e32 v142, s29, v179
	v_add_u32_e32 v160, s76, v179
	ds_read_b128 v[130:133], v142
	ds_read_b128 v[134:137], v142 offset:1024
	ds_read_b128 v[138:141], v142 offset:2048
	ds_read_b128 v[142:145], v142 offset:3072
	ds_read_b128 v[146:149], v160
	ds_read_b128 v[150:153], v160 offset:1024
	ds_read_b128 v[154:157], v160 offset:2048
	ds_read_b128 v[160:163], v160 offset:3072
	s_add_u32 s46, s46, 0x80000
	s_addc_u32 s47, s47, 0
	ds_read_b128 v[164:167], v200 offset:32768
	ds_read_b128 v[168:171], v200 offset:33792
	ds_read_b128 v[172:175], v200 offset:34816
	ds_read_b128 v[180:183], v200 offset:35840
	ds_read_b128 v[184:187], v200 offset:36864
	ds_read_b128 v[188:191], v200 offset:37888
	ds_read_b128 v[192:195], v200 offset:38912
	ds_read_b128 v[196:199], v200 offset:39936
	s_mov_b32 m0, s51
	v_lshl_add_u64 v[176:177], s[46:47], 0, v[158:159]
	s_add_u32 s46, s46, 0x40000
	s_addc_u32 s47, s47, 0
	global_load_lds_dwordx4 v[176:177], off
	s_mov_b32 m0, s52
	v_lshl_add_u64 v[176:177], s[46:47], 0, v[158:159]
	global_load_lds_dwordx4 v[176:177], off
	s_waitcnt vmcnt(8)
	s_waitcnt lgkmcnt(0)
	s_barrier
	s_waitcnt lgkmcnt(0)
	v_mfma_i32_16x16x64_i8 v[126:129], v[130:133], v[164:167], v[126:129]
	v_mfma_i32_16x16x64_i8 v[122:125], v[138:141], v[164:167], v[122:125]
	v_mfma_i32_16x16x64_i8 v[118:121], v[130:133], v[172:175], v[118:121]
	v_mfma_i32_16x16x64_i8 v[114:117], v[138:141], v[172:175], v[114:117]
	v_mfma_i32_16x16x64_i8 v[102:105], v[130:133], v[184:187], v[102:105]
	v_mfma_i32_16x16x64_i8 v[98:101], v[138:141], v[184:187], v[98:101]
	v_mfma_i32_16x16x64_i8 v[86:89], v[130:133], v[192:195], v[86:89]
	v_mfma_i32_16x16x64_i8 v[82:85], v[138:141], v[192:195], v[82:85]
	v_mfma_i32_16x16x64_i8 v[126:129], v[134:137], v[168:171], v[126:129]
	v_mfma_i32_16x16x64_i8 v[122:125], v[142:145], v[168:171], v[122:125]
	v_mfma_i32_16x16x64_i8 v[118:121], v[134:137], v[180:183], v[118:121]
	v_mfma_i32_16x16x64_i8 v[114:117], v[142:145], v[180:183], v[114:117]
	v_mfma_i32_16x16x64_i8 v[102:105], v[134:137], v[188:191], v[102:105]
	v_mfma_i32_16x16x64_i8 v[98:101], v[142:145], v[188:191], v[98:101]
	v_mfma_i32_16x16x64_i8 v[86:89], v[134:137], v[196:199], v[86:89]
	v_mfma_i32_16x16x64_i8 v[82:85], v[142:145], v[196:199], v[82:85]
	v_mfma_i32_16x16x64_i8 v[110:113], v[146:149], v[164:167], v[110:113]
	v_mfma_i32_16x16x64_i8 v[106:109], v[154:157], v[164:167], v[106:109]
	v_mfma_i32_16x16x64_i8 v[94:97], v[146:149], v[172:175], v[94:97]
	v_mfma_i32_16x16x64_i8 v[90:93], v[154:157], v[172:175], v[90:93]
	v_mfma_i32_16x16x64_i8 v[78:81], v[146:149], v[184:187], v[78:81]
	v_mfma_i32_16x16x64_i8 v[74:77], v[154:157], v[184:187], v[74:77]
	v_mfma_i32_16x16x64_i8 v[70:73], v[146:149], v[192:195], v[70:73]
	v_mfma_i32_16x16x64_i8 v[66:69], v[154:157], v[192:195], v[66:69]
	v_mfma_i32_16x16x64_i8 v[110:113], v[150:153], v[168:171], v[110:113]
	v_mfma_i32_16x16x64_i8 v[106:109], v[160:163], v[168:171], v[106:109]
	v_mfma_i32_16x16x64_i8 v[94:97], v[150:153], v[180:183], v[94:97]
	v_mfma_i32_16x16x64_i8 v[90:93], v[160:163], v[180:183], v[90:93]
	v_mfma_i32_16x16x64_i8 v[78:81], v[150:153], v[188:191], v[78:81]
	v_mfma_i32_16x16x64_i8 v[74:77], v[160:163], v[188:191], v[74:77]
	v_mfma_i32_16x16x64_i8 v[70:73], v[150:153], v[196:199], v[70:73]
	v_mfma_i32_16x16x64_i8 v[66:69], v[160:163], v[196:199], v[66:69]
	s_barrier
	s_add_u32 s46, s44, 0x80
	s_addc_u32 s47, s45, 0
	ds_read_b128 v[164:167], v200 offset:49152
	ds_read_b128 v[168:171], v200 offset:50176
	ds_read_b128 v[172:175], v200 offset:51200
	ds_read_b128 v[180:183], v200 offset:52224
	ds_read_b128 v[184:187], v200 offset:53248
	ds_read_b128 v[188:191], v200 offset:54272
	ds_read_b128 v[192:195], v200 offset:55296
	ds_read_b128 v[196:199], v200 offset:56320
	s_add_i32 s29, s29, s48
	v_lshl_add_u64 v[176:177], s[46:47], 0, v[202:203]
	s_mov_b32 m0, s29
	s_add_u32 s46, s46, 0x30000
	global_load_lds_dwordx4 v[176:177], off
	s_addc_u32 s47, s47, 0
	s_add_i32 m0, s29, 0x2000
	s_add_u32 s44, s44, 0x60080
	s_addc_u32 s45, s45, 0
	v_lshl_add_u64 v[176:177], s[46:47], 0, v[202:203]
	global_load_lds_dwordx4 v[176:177], off
	s_add_i32 s29, s76, s48
	v_lshl_add_u64 v[176:177], s[44:45], 0, v[202:203]
	s_add_u32 s44, s44, 0x30000
	s_mov_b32 m0, s29
	s_addc_u32 s45, s45, 0
	global_load_lds_dwordx4 v[176:177], off
	s_add_i32 m0, s29, 0x2000
	v_lshl_add_u64 v[176:177], s[44:45], 0, v[202:203]
	global_load_lds_dwordx4 v[176:177], off
	s_mov_b32 m0, s53
	v_lshl_add_u64 v[176:177], s[10:11], 0, v[158:159]
	s_add_u32 s10, s10, 0x40000
	s_addc_u32 s11, s11, 0
	global_load_lds_dwordx4 v[176:177], off
	s_mov_b32 m0, s54
	v_lshl_add_u64 v[176:177], s[10:11], 0, v[158:159]
	global_load_lds_dwordx4 v[176:177], off
	s_waitcnt vmcnt(8)
	s_waitcnt lgkmcnt(0)
	s_barrier
	s_waitcnt lgkmcnt(0)
	v_mfma_i32_16x16x64_i8 v[62:65], v[130:133], v[164:167], v[62:65]
	v_mfma_i32_16x16x64_i8 v[58:61], v[138:141], v[164:167], v[58:61]
	v_mfma_i32_16x16x64_i8 v[54:57], v[130:133], v[172:175], v[54:57]
	v_mfma_i32_16x16x64_i8 v[50:53], v[138:141], v[172:175], v[50:53]
	v_mfma_i32_16x16x64_i8 v[38:41], v[130:133], v[184:187], v[38:41]
	v_mfma_i32_16x16x64_i8 v[34:37], v[138:141], v[184:187], v[34:37]
	v_mfma_i32_16x16x64_i8 v[14:17], v[130:133], v[192:195], v[14:17]
	v_mfma_i32_16x16x64_i8 v[10:13], v[138:141], v[192:195], v[10:13]
	v_mfma_i32_16x16x64_i8 v[62:65], v[134:137], v[168:171], v[62:65]
	v_mfma_i32_16x16x64_i8 v[58:61], v[142:145], v[168:171], v[58:61]
	v_mfma_i32_16x16x64_i8 v[54:57], v[134:137], v[180:183], v[54:57]
	v_mfma_i32_16x16x64_i8 v[50:53], v[142:145], v[180:183], v[50:53]
	v_mfma_i32_16x16x64_i8 v[38:41], v[134:137], v[188:191], v[38:41]
	v_mfma_i32_16x16x64_i8 v[34:37], v[142:145], v[188:191], v[34:37]
	v_mfma_i32_16x16x64_i8 v[14:17], v[134:137], v[196:199], v[14:17]
	v_mfma_i32_16x16x64_i8 v[10:13], v[142:145], v[196:199], v[10:13]
	v_mfma_i32_16x16x64_i8 v[46:49], v[146:149], v[164:167], v[46:49]
	v_mfma_i32_16x16x64_i8 v[42:45], v[154:157], v[164:167], v[42:45]
	v_mfma_i32_16x16x64_i8 v[30:33], v[146:149], v[172:175], v[30:33]
	v_mfma_i32_16x16x64_i8 v[26:29], v[154:157], v[172:175], v[26:29]
	v_mfma_i32_16x16x64_i8 v[22:25], v[146:149], v[184:187], v[22:25]
	v_mfma_i32_16x16x64_i8 v[18:21], v[154:157], v[184:187], v[18:21]
	v_mfma_i32_16x16x64_i8 v[6:9], v[146:149], v[192:195], v[6:9]
	v_mfma_i32_16x16x64_i8 v[2:5], v[154:157], v[192:195], v[2:5]
	v_mfma_i32_16x16x64_i8 v[46:49], v[150:153], v[168:171], v[46:49]
	v_mfma_i32_16x16x64_i8 v[42:45], v[160:163], v[168:171], v[42:45]
	v_mfma_i32_16x16x64_i8 v[30:33], v[150:153], v[180:183], v[30:33]
	v_mfma_i32_16x16x64_i8 v[26:29], v[160:163], v[180:183], v[26:29]
	v_mfma_i32_16x16x64_i8 v[22:25], v[150:153], v[188:191], v[22:25]
	v_mfma_i32_16x16x64_i8 v[18:21], v[160:163], v[188:191], v[18:21]
	v_mfma_i32_16x16x64_i8 v[6:9], v[150:153], v[196:199], v[6:9]
	v_mfma_i32_16x16x64_i8 v[2:5], v[160:163], v[196:199], v[2:5]
	s_barrier
	s_add_u32 s74, s74, 0x100
	s_addc_u32 s75, s75, 0
	s_add_u32 s72, s72, 0x100
	s_addc_u32 s73, s73, 0
	s_cmp_ge_i32 s28, s69
	s_mov_b32 s10, s28
	s_cbranch_scc0 .LBB0_1026
	s_and_b64 vcc, exec, s[18:19]
	s_cbranch_vccz .LBB0_1029
	s_barrier

.Lop_nopf:
	ds_read_b128 v[130:133], v142
	ds_read_b128 v[134:137], v142 offset:1024
	ds_read_b128 v[138:141], v142 offset:2048
	ds_read_b128 v[142:145], v142 offset:3072
	ds_read_b128 v[146:149], v158
	ds_read_b128 v[150:153], v158 offset:1024
	ds_read_b128 v[154:157], v158 offset:2048
	ds_read_b128 v[158:161], v158 offset:3072
	s_mov_b64 s[74:75], s[46:47]
	ds_read_b128 v[162:165], v237
	ds_read_b128 v[166:169], v237 offset:1024
	ds_read_b128 v[170:173], v237 offset:2048
	ds_read_b128 v[174:177], v237 offset:3072
	ds_read_b128 v[178:181], v237 offset:4096
	ds_read_b128 v[182:185], v237 offset:5120
	ds_read_b128 v[188:191], v237 offset:6144
	ds_read_b128 v[192:195], v237 offset:7168
	s_add_i32 m0, s62, 0xc000
	v_lshl_add_u64 v[196:197], s[74:75], 0, v[186:187]
	s_add_u32 s74, s74, 0x40000
	s_addc_u32 s75, s75, 0
	global_load_lds_dwordx4 v[196:197], off
	s_add_i32 m0, s62, 0xe000
	v_lshl_add_u64 v[196:197], s[74:75], 0, v[186:187]
	global_load_lds_dwordx4 v[196:197], off
	s_waitcnt vmcnt(8)
	s_waitcnt lgkmcnt(0)
	s_barrier
	s_waitcnt lgkmcnt(0)
	v_mfma_f32_16x16x32_bf16 v[2:5], v[130:133], v[162:165], v[2:5]
	v_mfma_f32_16x16x32_bf16 v[6:9], v[138:141], v[162:165], v[6:9]
	v_mfma_f32_16x16x32_bf16 v[14:17], v[130:133], v[170:173], v[14:17]
	v_mfma_f32_16x16x32_bf16 v[22:25], v[138:141], v[170:173], v[22:25]
	v_mfma_f32_16x16x32_bf16 v[30:33], v[130:133], v[178:181], v[30:33]
	v_mfma_f32_16x16x32_bf16 v[38:41], v[138:141], v[178:181], v[38:41]
	v_mfma_f32_16x16x32_bf16 v[46:49], v[130:133], v[188:191], v[46:49]
	v_mfma_f32_16x16x32_bf16 v[54:57], v[138:141], v[188:191], v[54:57]
	v_mfma_f32_16x16x32_bf16 v[2:5], v[134:137], v[166:169], v[2:5]
	v_mfma_f32_16x16x32_bf16 v[6:9], v[142:145], v[166:169], v[6:9]
	v_mfma_f32_16x16x32_bf16 v[14:17], v[134:137], v[174:177], v[14:17]
	v_mfma_f32_16x16x32_bf16 v[22:25], v[142:145], v[174:177], v[22:25]
	v_mfma_f32_16x16x32_bf16 v[30:33], v[134:137], v[182:185], v[30:33]
	v_mfma_f32_16x16x32_bf16 v[38:41], v[142:145], v[182:185], v[38:41]
	v_mfma_f32_16x16x32_bf16 v[46:49], v[134:137], v[192:195], v[46:49]
	v_mfma_f32_16x16x32_bf16 v[54:57], v[142:145], v[192:195], v[54:57]
	v_mfma_f32_16x16x32_bf16 v[10:13], v[146:149], v[162:165], v[10:13]
	v_mfma_f32_16x16x32_bf16 v[18:21], v[154:157], v[162:165], v[18:21]
	v_mfma_f32_16x16x32_bf16 v[26:29], v[146:149], v[170:173], v[26:29]
	v_mfma_f32_16x16x32_bf16 v[34:37], v[154:157], v[170:173], v[34:37]
	v_mfma_f32_16x16x32_bf16 v[42:45], v[146:149], v[178:181], v[42:45]
	v_mfma_f32_16x16x32_bf16 v[50:53], v[154:157], v[178:181], v[50:53]
	v_mfma_f32_16x16x32_bf16 v[58:61], v[146:149], v[188:191], v[58:61]
	v_mfma_f32_16x16x32_bf16 v[62:65], v[154:157], v[188:191], v[62:65]
	v_mfma_f32_16x16x32_bf16 v[10:13], v[150:153], v[166:169], v[10:13]
	v_mfma_f32_16x16x32_bf16 v[18:21], v[158:161], v[166:169], v[18:21]
	v_mfma_f32_16x16x32_bf16 v[26:29], v[150:153], v[174:177], v[26:29]
	v_mfma_f32_16x16x32_bf16 v[34:37], v[158:161], v[174:177], v[34:37]
	v_mfma_f32_16x16x32_bf16 v[42:45], v[150:153], v[182:185], v[42:45]
	v_mfma_f32_16x16x32_bf16 v[50:53], v[158:161], v[182:185], v[50:53]
	v_mfma_f32_16x16x32_bf16 v[58:61], v[150:153], v[192:195], v[58:61]
	v_mfma_f32_16x16x32_bf16 v[62:65], v[158:161], v[192:195], v[62:65]
	s_barrier
	s_mov_b64 s[74:75], s[54:55]
	ds_read_b128 v[162:165], v237 offset:16384
	ds_read_b128 v[166:169], v237 offset:17408
	ds_read_b128 v[170:173], v237 offset:18432
	ds_read_b128 v[174:177], v237 offset:19456
	ds_read_b128 v[178:181], v237 offset:20480
	ds_read_b128 v[182:185], v237 offset:21504
	ds_read_b128 v[188:191], v237 offset:22528
	ds_read_b128 v[192:195], v237 offset:23552
	s_add_i32 s76, s76, s61
	v_lshl_add_u64 v[196:197], s[74:75], 0, v[202:203]
	s_add_u32 s74, s74, 0x40000
	s_mov_b32 m0, s76
	s_addc_u32 s75, s75, 0
	global_load_lds_dwordx4 v[196:197], off
	s_add_i32 m0, s76, 0x2000
	v_lshl_add_u64 v[196:197], s[74:75], 0, v[202:203]
	s_add_u32 s74, s54, 0x80000
	s_addc_u32 s75, s55, 0
	global_load_lds_dwordx4 v[196:197], off
	s_add_i32 s76, s77, s61
	v_lshl_add_u64 v[196:197], s[74:75], 0, v[202:203]
	s_add_u32 s74, s74, 0x40000
	s_mov_b32 m0, s76
	s_addc_u32 s75, s75, 0
	global_load_lds_dwordx4 v[196:197], off
	s_add_i32 m0, s76, 0x2000
	v_lshl_add_u64 v[196:197], s[74:75], 0, v[202:203]
	s_mov_b64 s[74:75], s[56:57]
	global_load_lds_dwordx4 v[196:197], off
	s_mov_b32 m0, s62
	v_lshl_add_u64 v[196:197], s[74:75], 0, v[186:187]
	s_add_u32 s74, s74, 0x40000
	s_addc_u32 s75, s75, 0
	global_load_lds_dwordx4 v[196:197], off
	s_mov_b32 m0, s63
	v_lshl_add_u64 v[196:197], s[74:75], 0, v[186:187]
	global_load_lds_dwordx4 v[196:197], off
	s_waitcnt vmcnt(8)
	s_waitcnt lgkmcnt(0)
	s_barrier
	s_waitcnt lgkmcnt(0)
	v_mfma_f32_16x16x32_bf16 v[66:69], v[130:133], v[162:165], v[66:69]
	v_mfma_f32_16x16x32_bf16 v[70:73], v[138:141], v[162:165], v[70:73]
	v_mfma_f32_16x16x32_bf16 v[74:77], v[130:133], v[170:173], v[74:77]
	v_mfma_f32_16x16x32_bf16 v[78:81], v[138:141], v[170:173], v[78:81]
	v_mfma_f32_16x16x32_bf16 v[86:89], v[130:133], v[178:181], v[86:89]
	v_mfma_f32_16x16x32_bf16 v[94:97], v[138:141], v[178:181], v[94:97]
	v_mfma_f32_16x16x32_bf16 v[102:105], v[130:133], v[188:191], v[102:105]
	v_mfma_f32_16x16x32_bf16 v[110:113], v[138:141], v[188:191], v[110:113]
	v_mfma_f32_16x16x32_bf16 v[66:69], v[134:137], v[166:169], v[66:69]
	v_mfma_f32_16x16x32_bf16 v[70:73], v[142:145], v[166:169], v[70:73]
	v_mfma_f32_16x16x32_bf16 v[74:77], v[134:137], v[174:177], v[74:77]
	v_mfma_f32_16x16x32_bf16 v[78:81], v[142:145], v[174:177], v[78:81]
	v_mfma_f32_16x16x32_bf16 v[86:89], v[134:137], v[182:185], v[86:89]
	v_mfma_f32_16x16x32_bf16 v[94:97], v[142:145], v[182:185], v[94:97]
	v_mfma_f32_16x16x32_bf16 v[102:105], v[134:137], v[192:195], v[102:105]
	v_mfma_f32_16x16x32_bf16 v[110:113], v[142:145], v[192:195], v[110:113]
	v_mfma_f32_16x16x32_bf16 v[82:85], v[146:149], v[162:165], v[82:85]
	v_mfma_f32_16x16x32_bf16 v[90:93], v[154:157], v[162:165], v[90:93]
	v_mfma_f32_16x16x32_bf16 v[98:101], v[146:149], v[170:173], v[98:101]
	v_mfma_f32_16x16x32_bf16 v[106:109], v[154:157], v[170:173], v[106:109]
	v_mfma_f32_16x16x32_bf16 v[114:117], v[146:149], v[178:181], v[114:117]
	v_mfma_f32_16x16x32_bf16 v[118:121], v[154:157], v[178:181], v[118:121]
	v_mfma_f32_16x16x32_bf16 v[122:125], v[146:149], v[188:191], v[122:125]
	v_mfma_f32_16x16x32_bf16 v[126:129], v[154:157], v[188:191], v[126:129]
	v_mfma_f32_16x16x32_bf16 v[82:85], v[150:153], v[166:169], v[82:85]
	v_mfma_f32_16x16x32_bf16 v[90:93], v[158:161], v[166:169], v[90:93]
	v_mfma_f32_16x16x32_bf16 v[98:101], v[150:153], v[174:177], v[98:101]
	v_mfma_f32_16x16x32_bf16 v[106:109], v[158:161], v[174:177], v[106:109]
	v_mfma_f32_16x16x32_bf16 v[114:117], v[150:153], v[182:185], v[114:117]
	v_mfma_f32_16x16x32_bf16 v[118:121], v[158:161], v[182:185], v[118:121]
	v_mfma_f32_16x16x32_bf16 v[122:125], v[150:153], v[192:195], v[122:125]
	v_mfma_f32_16x16x32_bf16 v[126:129], v[158:161], v[192:195], v[126:129]
	s_barrier
	s_add_i32 s74, 0, 0x18000
	s_add_i32 s75, 0, 0x1c000
	v_add_u32_e32 v142, s74, v207
	v_add_u32_e32 v158, s75, v207
	ds_read_b128 v[130:133], v142
	ds_read_b128 v[134:137], v142 offset:1024
	ds_read_b128 v[138:141], v142 offset:2048
	ds_read_b128 v[142:145], v142 offset:3072
	ds_read_b128 v[146:149], v158
	ds_read_b128 v[150:153], v158 offset:1024
	ds_read_b128 v[154:157], v158 offset:2048
	ds_read_b128 v[158:161], v158 offset:3072
	s_add_u32 s56, s56, 0x80000
	s_addc_u32 s57, s57, 0
	ds_read_b128 v[162:165], v237 offset:32768
	ds_read_b128 v[166:169], v237 offset:33792
	ds_read_b128 v[170:173], v237 offset:34816
	ds_read_b128 v[174:177], v237 offset:35840
	ds_read_b128 v[178:181], v237 offset:36864
	ds_read_b128 v[182:185], v237 offset:37888
	ds_read_b128 v[188:191], v237 offset:38912
	ds_read_b128 v[192:195], v237 offset:39936
	s_mov_b32 m0, s64
	v_lshl_add_u64 v[196:197], s[56:57], 0, v[186:187]
	s_add_u32 s56, s56, 0x40000
	s_addc_u32 s57, s57, 0
	global_load_lds_dwordx4 v[196:197], off
	s_mov_b32 m0, s65
	v_lshl_add_u64 v[196:197], s[56:57], 0, v[186:187]
	global_load_lds_dwordx4 v[196:197], off
	s_waitcnt vmcnt(8)
	s_waitcnt lgkmcnt(0)
	s_barrier
	s_waitcnt lgkmcnt(0)
	v_mfma_f32_16x16x32_bf16 v[2:5], v[130:133], v[162:165], v[2:5]
	v_mfma_f32_16x16x32_bf16 v[6:9], v[138:141], v[162:165], v[6:9]
	v_mfma_f32_16x16x32_bf16 v[14:17], v[130:133], v[170:173], v[14:17]
	v_mfma_f32_16x16x32_bf16 v[22:25], v[138:141], v[170:173], v[22:25]
	v_mfma_f32_16x16x32_bf16 v[30:33], v[130:133], v[178:181], v[30:33]
	v_mfma_f32_16x16x32_bf16 v[38:41], v[138:141], v[178:181], v[38:41]
	v_mfma_f32_16x16x32_bf16 v[46:49], v[130:133], v[188:191], v[46:49]
	v_mfma_f32_16x16x32_bf16 v[54:57], v[138:141], v[188:191], v[54:57]
	v_mfma_f32_16x16x32_bf16 v[2:5], v[134:137], v[166:169], v[2:5]
	v_mfma_f32_16x16x32_bf16 v[6:9], v[142:145], v[166:169], v[6:9]
	v_mfma_f32_16x16x32_bf16 v[14:17], v[134:137], v[174:177], v[14:17]
	v_mfma_f32_16x16x32_bf16 v[22:25], v[142:145], v[174:177], v[22:25]
	v_mfma_f32_16x16x32_bf16 v[30:33], v[134:137], v[182:185], v[30:33]
	v_mfma_f32_16x16x32_bf16 v[38:41], v[142:145], v[182:185], v[38:41]
	v_mfma_f32_16x16x32_bf16 v[46:49], v[134:137], v[192:195], v[46:49]
	v_mfma_f32_16x16x32_bf16 v[54:57], v[142:145], v[192:195], v[54:57]
	v_mfma_f32_16x16x32_bf16 v[10:13], v[146:149], v[162:165], v[10:13]
	v_mfma_f32_16x16x32_bf16 v[18:21], v[154:157], v[162:165], v[18:21]
	v_mfma_f32_16x16x32_bf16 v[26:29], v[146:149], v[170:173], v[26:29]
	v_mfma_f32_16x16x32_bf16 v[34:37], v[154:157], v[170:173], v[34:37]
	v_mfma_f32_16x16x32_bf16 v[42:45], v[146:149], v[178:181], v[42:45]
	v_mfma_f32_16x16x32_bf16 v[50:53], v[154:157], v[178:181], v[50:53]
	v_mfma_f32_16x16x32_bf16 v[58:61], v[146:149], v[188:191], v[58:61]
	v_mfma_f32_16x16x32_bf16 v[62:65], v[154:157], v[188:191], v[62:65]
	v_mfma_f32_16x16x32_bf16 v[10:13], v[150:153], v[166:169], v[10:13]
	v_mfma_f32_16x16x32_bf16 v[18:21], v[158:161], v[166:169], v[18:21]
	v_mfma_f32_16x16x32_bf16 v[26:29], v[150:153], v[174:177], v[26:29]
	v_mfma_f32_16x16x32_bf16 v[34:37], v[158:161], v[174:177], v[34:37]
	v_mfma_f32_16x16x32_bf16 v[42:45], v[150:153], v[182:185], v[42:45]
	v_mfma_f32_16x16x32_bf16 v[50:53], v[158:161], v[182:185], v[50:53]
	v_mfma_f32_16x16x32_bf16 v[58:61], v[150:153], v[192:195], v[58:61]
	v_mfma_f32_16x16x32_bf16 v[62:65], v[158:161], v[192:195], v[62:65]
	s_barrier
	s_add_u32 s56, s54, 0x80
	s_addc_u32 s57, s55, 0
	ds_read_b128 v[162:165], v237 offset:49152
	ds_read_b128 v[166:169], v237 offset:50176
	ds_read_b128 v[170:173], v237 offset:51200
	ds_read_b128 v[174:177], v237 offset:52224
	ds_read_b128 v[178:181], v237 offset:53248
	ds_read_b128 v[182:185], v237 offset:54272
	ds_read_b128 v[188:191], v237 offset:55296
	ds_read_b128 v[192:195], v237 offset:56320
	s_add_i32 s74, s74, s61
	v_lshl_add_u64 v[196:197], s[56:57], 0, v[202:203]
	s_mov_b32 m0, s74
	s_add_u32 s56, s56, 0x40000
	global_load_lds_dwordx4 v[196:197], off
	s_addc_u32 s57, s57, 0
	s_add_i32 m0, s74, 0x2000
	s_add_u32 s54, s54, 0x80080
	s_addc_u32 s55, s55, 0
	v_lshl_add_u64 v[196:197], s[56:57], 0, v[202:203]
	global_load_lds_dwordx4 v[196:197], off
	s_add_i32 s56, s75, s61
	v_lshl_add_u64 v[196:197], s[54:55], 0, v[202:203]
	s_add_u32 s54, s54, 0x40000
	s_mov_b32 m0, s56
	s_addc_u32 s55, s55, 0
	global_load_lds_dwordx4 v[196:197], off
	s_add_i32 m0, s56, 0x2000
	v_lshl_add_u64 v[196:197], s[54:55], 0, v[202:203]
	global_load_lds_dwordx4 v[196:197], off
	s_mov_b32 m0, s66
	v_lshl_add_u64 v[196:197], s[48:49], 0, v[186:187]
	s_add_u32 s48, s48, 0x40000
	s_addc_u32 s49, s49, 0
	global_load_lds_dwordx4 v[196:197], off
	s_mov_b32 m0, s67
	v_lshl_add_u64 v[196:197], s[48:49], 0, v[186:187]
	global_load_lds_dwordx4 v[196:197], off
	s_waitcnt vmcnt(8)
	s_waitcnt lgkmcnt(0)
	s_barrier
	s_waitcnt lgkmcnt(0)
	v_mfma_f32_16x16x32_bf16 v[66:69], v[130:133], v[162:165], v[66:69]
	v_mfma_f32_16x16x32_bf16 v[70:73], v[138:141], v[162:165], v[70:73]
	v_mfma_f32_16x16x32_bf16 v[74:77], v[130:133], v[170:173], v[74:77]
	v_mfma_f32_16x16x32_bf16 v[78:81], v[138:141], v[170:173], v[78:81]
	v_mfma_f32_16x16x32_bf16 v[86:89], v[130:133], v[178:181], v[86:89]
	v_mfma_f32_16x16x32_bf16 v[94:97], v[138:141], v[178:181], v[94:97]
	v_mfma_f32_16x16x32_bf16 v[102:105], v[130:133], v[188:191], v[102:105]
	v_mfma_f32_16x16x32_bf16 v[110:113], v[138:141], v[188:191], v[110:113]
	v_mfma_f32_16x16x32_bf16 v[66:69], v[134:137], v[166:169], v[66:69]
	v_mfma_f32_16x16x32_bf16 v[70:73], v[142:145], v[166:169], v[70:73]
	v_mfma_f32_16x16x32_bf16 v[74:77], v[134:137], v[174:177], v[74:77]
	v_mfma_f32_16x16x32_bf16 v[78:81], v[142:145], v[174:177], v[78:81]
	v_mfma_f32_16x16x32_bf16 v[86:89], v[134:137], v[182:185], v[86:89]
	v_mfma_f32_16x16x32_bf16 v[94:97], v[142:145], v[182:185], v[94:97]
	v_mfma_f32_16x16x32_bf16 v[102:105], v[134:137], v[192:195], v[102:105]
	v_mfma_f32_16x16x32_bf16 v[110:113], v[142:145], v[192:195], v[110:113]
	v_mfma_f32_16x16x32_bf16 v[82:85], v[146:149], v[162:165], v[82:85]
	v_mfma_f32_16x16x32_bf16 v[90:93], v[154:157], v[162:165], v[90:93]
	v_mfma_f32_16x16x32_bf16 v[98:101], v[146:149], v[170:173], v[98:101]
	v_mfma_f32_16x16x32_bf16 v[106:109], v[154:157], v[170:173], v[106:109]
	v_mfma_f32_16x16x32_bf16 v[114:117], v[146:149], v[178:181], v[114:117]
	v_mfma_f32_16x16x32_bf16 v[118:121], v[154:157], v[178:181], v[118:121]
	v_mfma_f32_16x16x32_bf16 v[122:125], v[146:149], v[188:191], v[122:125]
	v_mfma_f32_16x16x32_bf16 v[126:129], v[154:157], v[188:191], v[126:129]
	v_mfma_f32_16x16x32_bf16 v[82:85], v[150:153], v[166:169], v[82:85]
	v_mfma_f32_16x16x32_bf16 v[90:93], v[158:161], v[166:169], v[90:93]
	v_mfma_f32_16x16x32_bf16 v[98:101], v[150:153], v[174:177], v[98:101]
	v_mfma_f32_16x16x32_bf16 v[106:109], v[158:161], v[174:177], v[106:109]
	v_mfma_f32_16x16x32_bf16 v[114:117], v[150:153], v[182:185], v[114:117]
	v_mfma_f32_16x16x32_bf16 v[118:121], v[158:161], v[182:185], v[118:121]
	v_mfma_f32_16x16x32_bf16 v[122:125], v[150:153], v[192:195], v[122:125]
	v_mfma_f32_16x16x32_bf16 v[126:129], v[158:161], v[192:195], v[126:129]
	s_barrier
	s_add_i32 s29, s29, 2
	s_add_u32 s7, s7, 0x100
	s_addc_u32 s21, s21, 0
	s_add_u32 s27, s27, 0x100
	s_addc_u32 s28, s28, 0
	s_add_u32 s46, s46, 0x100
	s_addc_u32 s47, s47, 0
	s_cmp_gt_u32 s29, 29
	s_cbranch_scc0 .LBB0_1096
	s_and_b64 vcc, exec, s[18:19]
	s_cbranch_vccz .LBB0_1099
	s_barrier

.Lfu_nopf:
	s_add_u32 s46, s50, 0x80
	s_addc_u32 s47, s51, 0
	s_add_i32 s68, 0, 0x10000
	s_add_i32 s69, 0, 0x14000
	v_add_u32_e32 v142, s68, v208
	v_add_u32_e32 v158, s69, v208
	ds_read_b128 v[130:133], v142
	ds_read_b128 v[134:137], v142 offset:1024
	ds_read_b128 v[138:141], v142 offset:2048
	ds_read_b128 v[142:145], v142 offset:3072
	ds_read_b128 v[146:149], v158
	ds_read_b128 v[150:153], v158 offset:1024
	ds_read_b128 v[154:157], v158 offset:2048
	ds_read_b128 v[158:161], v158 offset:3072
	s_add_u32 s66, s23, 0x7ff80
	s_addc_u32 s67, s62, 0
	ds_read_b128 v[162:165], v210
	ds_read_b128 v[166:169], v210 offset:1024
	ds_read_b128 v[170:173], v210 offset:2048
	ds_read_b128 v[174:177], v210 offset:3072
	ds_read_b128 v[180:183], v210 offset:4096
	ds_read_b128 v[184:187], v210 offset:5120
	ds_read_b128 v[188:191], v210 offset:6144
	ds_read_b128 v[192:195], v210 offset:7168
	s_add_i32 m0, s52, 0xc000
	v_lshl_add_u64 v[196:197], s[66:67], 0, v[178:179]
	s_add_u32 s66, s66, 0x40000
	s_addc_u32 s67, s67, 0
	global_load_lds_dwordx4 v[196:197], off
	s_add_i32 m0, s52, 0xe000
	v_lshl_add_u64 v[196:197], s[66:67], 0, v[178:179]
	global_load_lds_dwordx4 v[196:197], off
	s_waitcnt vmcnt(8)
	s_waitcnt lgkmcnt(0)
	s_barrier
	s_waitcnt lgkmcnt(0)
	v_mfma_i32_16x16x64_i8 v[126:129], v[130:133], v[162:165], v[126:129]
	v_mfma_i32_16x16x64_i8 v[118:121], v[138:141], v[162:165], v[118:121]
	v_mfma_i32_16x16x64_i8 v[110:113], v[130:133], v[170:173], v[110:113]
	v_mfma_i32_16x16x64_i8 v[102:105], v[138:141], v[170:173], v[102:105]
	v_mfma_i32_16x16x64_i8 v[94:97], v[130:133], v[180:183], v[94:97]
	v_mfma_i32_16x16x64_i8 v[86:89], v[138:141], v[180:183], v[86:89]
	v_mfma_i32_16x16x64_i8 v[78:81], v[130:133], v[188:191], v[78:81]
	v_mfma_i32_16x16x64_i8 v[70:73], v[138:141], v[188:191], v[70:73]
	v_mfma_i32_16x16x64_i8 v[126:129], v[134:137], v[166:169], v[126:129]
	v_mfma_i32_16x16x64_i8 v[118:121], v[142:145], v[166:169], v[118:121]
	v_mfma_i32_16x16x64_i8 v[110:113], v[134:137], v[174:177], v[110:113]
	v_mfma_i32_16x16x64_i8 v[102:105], v[142:145], v[174:177], v[102:105]
	v_mfma_i32_16x16x64_i8 v[94:97], v[134:137], v[184:187], v[94:97]
	v_mfma_i32_16x16x64_i8 v[86:89], v[142:145], v[184:187], v[86:89]
	v_mfma_i32_16x16x64_i8 v[78:81], v[134:137], v[192:195], v[78:81]
	v_mfma_i32_16x16x64_i8 v[70:73], v[142:145], v[192:195], v[70:73]
	v_mfma_i32_16x16x64_i8 v[122:125], v[146:149], v[162:165], v[122:125]
	v_mfma_i32_16x16x64_i8 v[114:117], v[154:157], v[162:165], v[114:117]
	v_mfma_i32_16x16x64_i8 v[106:109], v[146:149], v[170:173], v[106:109]
	v_mfma_i32_16x16x64_i8 v[98:101], v[154:157], v[170:173], v[98:101]
	v_mfma_i32_16x16x64_i8 v[90:93], v[146:149], v[180:183], v[90:93]
	v_mfma_i32_16x16x64_i8 v[82:85], v[154:157], v[180:183], v[82:85]
	v_mfma_i32_16x16x64_i8 v[74:77], v[146:149], v[188:191], v[74:77]
	v_mfma_i32_16x16x64_i8 v[66:69], v[154:157], v[188:191], v[66:69]
	v_mfma_i32_16x16x64_i8 v[122:125], v[150:153], v[166:169], v[122:125]
	v_mfma_i32_16x16x64_i8 v[114:117], v[158:161], v[166:169], v[114:117]
	v_mfma_i32_16x16x64_i8 v[106:109], v[150:153], v[174:177], v[106:109]
	v_mfma_i32_16x16x64_i8 v[98:101], v[158:161], v[174:177], v[98:101]
	v_mfma_i32_16x16x64_i8 v[90:93], v[150:153], v[184:187], v[90:93]
	v_mfma_i32_16x16x64_i8 v[82:85], v[158:161], v[184:187], v[82:85]
	v_mfma_i32_16x16x64_i8 v[74:77], v[150:153], v[192:195], v[74:77]
	v_mfma_i32_16x16x64_i8 v[66:69], v[158:161], v[192:195], v[66:69]
	s_barrier
	s_mov_b64 s[66:67], s[48:49]
	ds_read_b128 v[162:165], v210 offset:16384
	ds_read_b128 v[166:169], v210 offset:17408
	ds_read_b128 v[170:173], v210 offset:18432
	ds_read_b128 v[174:177], v210 offset:19456
	ds_read_b128 v[180:183], v210 offset:20480
	ds_read_b128 v[184:187], v210 offset:21504
	ds_read_b128 v[188:191], v210 offset:22528
	ds_read_b128 v[192:195], v210 offset:23552
	s_add_i32 s68, s68, s31
	v_lshl_add_u64 v[196:197], s[66:67], 0, v[202:203]
	s_add_u32 s66, s66, 0x20000
	s_mov_b32 m0, s68
	s_addc_u32 s67, s67, 0
	global_load_lds_dwordx4 v[196:197], off
	s_add_i32 m0, s68, 0x2000
	v_lshl_add_u64 v[196:197], s[66:67], 0, v[202:203]
	s_add_u32 s66, s48, 0x40000
	s_addc_u32 s67, s49, 0
	global_load_lds_dwordx4 v[196:197], off
	s_add_i32 s68, s69, s31
	v_lshl_add_u64 v[196:197], s[66:67], 0, v[202:203]
	s_add_u32 s66, s66, 0x20000
	s_mov_b32 m0, s68
	s_addc_u32 s67, s67, 0
	global_load_lds_dwordx4 v[196:197], off
	s_add_i32 m0, s68, 0x2000
	v_lshl_add_u64 v[196:197], s[66:67], 0, v[202:203]
	s_mov_b64 s[66:67], s[50:51]
	global_load_lds_dwordx4 v[196:197], off
	s_mov_b32 m0, s52
	v_lshl_add_u64 v[196:197], s[66:67], 0, v[178:179]
	s_add_u32 s66, s66, 0x40000
	s_addc_u32 s67, s67, 0
	global_load_lds_dwordx4 v[196:197], off
	s_mov_b32 m0, s53
	v_lshl_add_u64 v[196:197], s[66:67], 0, v[178:179]
	global_load_lds_dwordx4 v[196:197], off
	s_waitcnt vmcnt(8)
	s_waitcnt lgkmcnt(0)
	s_barrier
	s_waitcnt lgkmcnt(0)
	v_mfma_i32_16x16x64_i8 v[62:65], v[130:133], v[162:165], v[62:65]
	v_mfma_i32_16x16x64_i8 v[54:57], v[138:141], v[162:165], v[54:57]
	v_mfma_i32_16x16x64_i8 v[46:49], v[130:133], v[170:173], v[46:49]
	v_mfma_i32_16x16x64_i8 v[38:41], v[138:141], v[170:173], v[38:41]
	v_mfma_i32_16x16x64_i8 v[30:33], v[130:133], v[180:183], v[30:33]
	v_mfma_i32_16x16x64_i8 v[22:25], v[138:141], v[180:183], v[22:25]
	v_mfma_i32_16x16x64_i8 v[14:17], v[130:133], v[188:191], v[14:17]
	v_mfma_i32_16x16x64_i8 v[6:9], v[138:141], v[188:191], v[6:9]
	v_mfma_i32_16x16x64_i8 v[62:65], v[134:137], v[166:169], v[62:65]
	v_mfma_i32_16x16x64_i8 v[54:57], v[142:145], v[166:169], v[54:57]
	v_mfma_i32_16x16x64_i8 v[46:49], v[134:137], v[174:177], v[46:49]
	v_mfma_i32_16x16x64_i8 v[38:41], v[142:145], v[174:177], v[38:41]
	v_mfma_i32_16x16x64_i8 v[30:33], v[134:137], v[184:187], v[30:33]
	v_mfma_i32_16x16x64_i8 v[22:25], v[142:145], v[184:187], v[22:25]
	v_mfma_i32_16x16x64_i8 v[14:17], v[134:137], v[192:195], v[14:17]
	v_mfma_i32_16x16x64_i8 v[6:9], v[142:145], v[192:195], v[6:9]
	v_mfma_i32_16x16x64_i8 v[58:61], v[146:149], v[162:165], v[58:61]
	v_mfma_i32_16x16x64_i8 v[50:53], v[154:157], v[162:165], v[50:53]
	v_mfma_i32_16x16x64_i8 v[42:45], v[146:149], v[170:173], v[42:45]
	v_mfma_i32_16x16x64_i8 v[34:37], v[154:157], v[170:173], v[34:37]
	v_mfma_i32_16x16x64_i8 v[26:29], v[146:149], v[180:183], v[26:29]
	v_mfma_i32_16x16x64_i8 v[18:21], v[154:157], v[180:183], v[18:21]
	v_mfma_i32_16x16x64_i8 v[10:13], v[146:149], v[188:191], v[10:13]
	v_mfma_i32_16x16x64_i8 v[2:5], v[154:157], v[188:191], v[2:5]
	v_mfma_i32_16x16x64_i8 v[58:61], v[150:153], v[166:169], v[58:61]
	v_mfma_i32_16x16x64_i8 v[50:53], v[158:161], v[166:169], v[50:53]
	v_mfma_i32_16x16x64_i8 v[42:45], v[150:153], v[174:177], v[42:45]
	v_mfma_i32_16x16x64_i8 v[34:37], v[158:161], v[174:177], v[34:37]
	v_mfma_i32_16x16x64_i8 v[26:29], v[150:153], v[184:187], v[26:29]
	v_mfma_i32_16x16x64_i8 v[18:21], v[158:161], v[184:187], v[18:21]
	v_mfma_i32_16x16x64_i8 v[10:13], v[150:153], v[192:195], v[10:13]
	v_mfma_i32_16x16x64_i8 v[2:5], v[158:161], v[192:195], v[2:5]
	s_barrier
	s_add_i32 s66, 0, 0x18000
	s_add_i32 s67, 0, 0x1c000
	v_add_u32_e32 v142, s66, v208
	v_add_u32_e32 v158, s67, v208
	ds_read_b128 v[130:133], v142
	ds_read_b128 v[134:137], v142 offset:1024
	ds_read_b128 v[138:141], v142 offset:2048
	ds_read_b128 v[142:145], v142 offset:3072
	ds_read_b128 v[146:149], v158
	ds_read_b128 v[150:153], v158 offset:1024
	ds_read_b128 v[154:157], v158 offset:2048
	ds_read_b128 v[158:161], v158 offset:3072
	s_add_u32 s50, s50, 0x80000
	s_addc_u32 s51, s51, 0
	ds_read_b128 v[162:165], v210 offset:32768
	ds_read_b128 v[166:169], v210 offset:33792
	ds_read_b128 v[170:173], v210 offset:34816
	ds_read_b128 v[174:177], v210 offset:35840
	ds_read_b128 v[180:183], v210 offset:36864
	ds_read_b128 v[184:187], v210 offset:37888
	ds_read_b128 v[188:191], v210 offset:38912
	ds_read_b128 v[192:195], v210 offset:39936
	s_mov_b32 m0, s54
	v_lshl_add_u64 v[196:197], s[50:51], 0, v[178:179]
	s_add_u32 s50, s50, 0x40000
	s_addc_u32 s51, s51, 0
	global_load_lds_dwordx4 v[196:197], off
	s_mov_b32 m0, s55
	v_lshl_add_u64 v[196:197], s[50:51], 0, v[178:179]
	global_load_lds_dwordx4 v[196:197], off
	s_waitcnt vmcnt(8)
	s_waitcnt lgkmcnt(0)
	s_barrier
	s_waitcnt lgkmcnt(0)
	v_mfma_i32_16x16x64_i8 v[126:129], v[130:133], v[162:165], v[126:129]
	v_mfma_i32_16x16x64_i8 v[118:121], v[138:141], v[162:165], v[118:121]
	v_mfma_i32_16x16x64_i8 v[110:113], v[130:133], v[170:173], v[110:113]
	v_mfma_i32_16x16x64_i8 v[102:105], v[138:141], v[170:173], v[102:105]
	v_mfma_i32_16x16x64_i8 v[94:97], v[130:133], v[180:183], v[94:97]
	v_mfma_i32_16x16x64_i8 v[86:89], v[138:141], v[180:183], v[86:89]
	v_mfma_i32_16x16x64_i8 v[78:81], v[130:133], v[188:191], v[78:81]
	v_mfma_i32_16x16x64_i8 v[70:73], v[138:141], v[188:191], v[70:73]
	v_mfma_i32_16x16x64_i8 v[126:129], v[134:137], v[166:169], v[126:129]
	v_mfma_i32_16x16x64_i8 v[118:121], v[142:145], v[166:169], v[118:121]
	v_mfma_i32_16x16x64_i8 v[110:113], v[134:137], v[174:177], v[110:113]
	v_mfma_i32_16x16x64_i8 v[102:105], v[142:145], v[174:177], v[102:105]
	v_mfma_i32_16x16x64_i8 v[94:97], v[134:137], v[184:187], v[94:97]
	v_mfma_i32_16x16x64_i8 v[86:89], v[142:145], v[184:187], v[86:89]
	v_mfma_i32_16x16x64_i8 v[78:81], v[134:137], v[192:195], v[78:81]
	v_mfma_i32_16x16x64_i8 v[70:73], v[142:145], v[192:195], v[70:73]
	v_mfma_i32_16x16x64_i8 v[122:125], v[146:149], v[162:165], v[122:125]
	v_mfma_i32_16x16x64_i8 v[114:117], v[154:157], v[162:165], v[114:117]
	v_mfma_i32_16x16x64_i8 v[106:109], v[146:149], v[170:173], v[106:109]
	v_mfma_i32_16x16x64_i8 v[98:101], v[154:157], v[170:173], v[98:101]
	v_mfma_i32_16x16x64_i8 v[90:93], v[146:149], v[180:183], v[90:93]
	v_mfma_i32_16x16x64_i8 v[82:85], v[154:157], v[180:183], v[82:85]
	v_mfma_i32_16x16x64_i8 v[74:77], v[146:149], v[188:191], v[74:77]
	v_mfma_i32_16x16x64_i8 v[66:69], v[154:157], v[188:191], v[66:69]
	v_mfma_i32_16x16x64_i8 v[122:125], v[150:153], v[166:169], v[122:125]
	v_mfma_i32_16x16x64_i8 v[114:117], v[158:161], v[166:169], v[114:117]
	v_mfma_i32_16x16x64_i8 v[106:109], v[150:153], v[174:177], v[106:109]
	v_mfma_i32_16x16x64_i8 v[98:101], v[158:161], v[174:177], v[98:101]
	v_mfma_i32_16x16x64_i8 v[90:93], v[150:153], v[184:187], v[90:93]
	v_mfma_i32_16x16x64_i8 v[82:85], v[158:161], v[184:187], v[82:85]
	v_mfma_i32_16x16x64_i8 v[74:77], v[150:153], v[192:195], v[74:77]
	v_mfma_i32_16x16x64_i8 v[66:69], v[158:161], v[192:195], v[66:69]
	s_barrier
	s_add_u32 s50, s48, 0x80
	s_addc_u32 s51, s49, 0
	ds_read_b128 v[162:165], v210 offset:49152
	ds_read_b128 v[166:169], v210 offset:50176
	ds_read_b128 v[170:173], v210 offset:51200
	ds_read_b128 v[174:177], v210 offset:52224
	ds_read_b128 v[180:183], v210 offset:53248
	ds_read_b128 v[184:187], v210 offset:54272
	ds_read_b128 v[188:191], v210 offset:55296
	ds_read_b128 v[192:195], v210 offset:56320
	s_add_i32 s66, s66, s31
	v_lshl_add_u64 v[196:197], s[50:51], 0, v[202:203]
	s_mov_b32 m0, s66
	s_add_u32 s50, s50, 0x20000
	global_load_lds_dwordx4 v[196:197], off
	s_addc_u32 s51, s51, 0
	s_add_i32 m0, s66, 0x2000
	s_add_u32 s48, s48, 0x40080
	s_addc_u32 s49, s49, 0
	v_lshl_add_u64 v[196:197], s[50:51], 0, v[202:203]
	global_load_lds_dwordx4 v[196:197], off
	s_add_i32 s50, s67, s31
	v_lshl_add_u64 v[196:197], s[48:49], 0, v[202:203]
	s_add_u32 s48, s48, 0x20000
	s_mov_b32 m0, s50
	s_addc_u32 s49, s49, 0
	global_load_lds_dwordx4 v[196:197], off
	s_add_i32 m0, s50, 0x2000
	v_lshl_add_u64 v[196:197], s[48:49], 0, v[202:203]
	global_load_lds_dwordx4 v[196:197], off
	s_mov_b32 m0, s56
	v_lshl_add_u64 v[196:197], s[46:47], 0, v[178:179]
	s_add_u32 s46, s46, 0x40000
	s_addc_u32 s47, s47, 0
	global_load_lds_dwordx4 v[196:197], off
	s_mov_b32 m0, s57
	v_lshl_add_u64 v[196:197], s[46:47], 0, v[178:179]
	global_load_lds_dwordx4 v[196:197], off
	s_waitcnt vmcnt(8)
	s_waitcnt lgkmcnt(0)
	s_barrier
	s_waitcnt lgkmcnt(0)
	v_mfma_i32_16x16x64_i8 v[62:65], v[130:133], v[162:165], v[62:65]
	v_mfma_i32_16x16x64_i8 v[54:57], v[138:141], v[162:165], v[54:57]
	v_mfma_i32_16x16x64_i8 v[46:49], v[130:133], v[170:173], v[46:49]
	v_mfma_i32_16x16x64_i8 v[38:41], v[138:141], v[170:173], v[38:41]
	v_mfma_i32_16x16x64_i8 v[30:33], v[130:133], v[180:183], v[30:33]
	v_mfma_i32_16x16x64_i8 v[22:25], v[138:141], v[180:183], v[22:25]
	v_mfma_i32_16x16x64_i8 v[14:17], v[130:133], v[188:191], v[14:17]
	v_mfma_i32_16x16x64_i8 v[6:9], v[138:141], v[188:191], v[6:9]
	v_mfma_i32_16x16x64_i8 v[62:65], v[134:137], v[166:169], v[62:65]
	v_mfma_i32_16x16x64_i8 v[54:57], v[142:145], v[166:169], v[54:57]
	v_mfma_i32_16x16x64_i8 v[46:49], v[134:137], v[174:177], v[46:49]
	v_mfma_i32_16x16x64_i8 v[38:41], v[142:145], v[174:177], v[38:41]
	v_mfma_i32_16x16x64_i8 v[30:33], v[134:137], v[184:187], v[30:33]
	v_mfma_i32_16x16x64_i8 v[22:25], v[142:145], v[184:187], v[22:25]
	v_mfma_i32_16x16x64_i8 v[14:17], v[134:137], v[192:195], v[14:17]
	v_mfma_i32_16x16x64_i8 v[6:9], v[142:145], v[192:195], v[6:9]
	v_mfma_i32_16x16x64_i8 v[58:61], v[146:149], v[162:165], v[58:61]
	v_mfma_i32_16x16x64_i8 v[50:53], v[154:157], v[162:165], v[50:53]
	v_mfma_i32_16x16x64_i8 v[42:45], v[146:149], v[170:173], v[42:45]
	v_mfma_i32_16x16x64_i8 v[34:37], v[154:157], v[170:173], v[34:37]
	v_mfma_i32_16x16x64_i8 v[26:29], v[146:149], v[180:183], v[26:29]
	v_mfma_i32_16x16x64_i8 v[18:21], v[154:157], v[180:183], v[18:21]
	v_mfma_i32_16x16x64_i8 v[10:13], v[146:149], v[188:191], v[10:13]
	v_mfma_i32_16x16x64_i8 v[2:5], v[154:157], v[188:191], v[2:5]
	v_mfma_i32_16x16x64_i8 v[58:61], v[150:153], v[166:169], v[58:61]
	v_mfma_i32_16x16x64_i8 v[50:53], v[158:161], v[166:169], v[50:53]
	v_mfma_i32_16x16x64_i8 v[42:45], v[150:153], v[174:177], v[42:45]
	v_mfma_i32_16x16x64_i8 v[34:37], v[158:161], v[174:177], v[34:37]
	v_mfma_i32_16x16x64_i8 v[26:29], v[150:153], v[184:187], v[26:29]
	v_mfma_i32_16x16x64_i8 v[18:21], v[158:161], v[184:187], v[18:21]
	v_mfma_i32_16x16x64_i8 v[10:13], v[150:153], v[192:195], v[10:13]
	v_mfma_i32_16x16x64_i8 v[2:5], v[158:161], v[192:195], v[2:5]
	s_barrier
	s_add_i32 s65, s65, 2
	s_add_u32 s23, s23, 0x100
	s_addc_u32 s62, s62, 0
	s_add_u32 s63, s63, 0x100
	s_addc_u32 s64, s64, 0
	s_cmp_gt_u32 s65, 13
	s_cbranch_scc0 .LBB0_1214
	s_and_b64 vcc, exec, s[18:19]
	s_cbranch_vccz .LBB0_1217
	s_barrier

.Lfd_nopf:
	ds_read_b128 v[130:133], v142
	ds_read_b128 v[134:137], v142 offset:1024
	ds_read_b128 v[138:141], v142 offset:2048
	ds_read_b128 v[142:145], v142 offset:3072
	ds_read_b128 v[146:149], v158
	ds_read_b128 v[150:153], v158 offset:1024
	ds_read_b128 v[154:157], v158 offset:2048
	ds_read_b128 v[158:161], v158 offset:3072
	s_mov_b64 s[72:73], s[44:45]
	ds_read_b128 v[162:165], v237
	ds_read_b128 v[166:169], v237 offset:1024
	ds_read_b128 v[170:173], v237 offset:2048
	ds_read_b128 v[174:177], v237 offset:3072
	ds_read_b128 v[178:181], v237 offset:4096
	ds_read_b128 v[182:185], v237 offset:5120
	ds_read_b128 v[188:191], v237 offset:6144
	ds_read_b128 v[192:195], v237 offset:7168
	s_add_i32 m0, s58, 0xc000
	v_lshl_add_u64 v[196:197], s[72:73], 0, v[186:187]
	s_add_u32 s72, s72, 0xb0000
	s_addc_u32 s73, s73, 0
	global_load_lds_dwordx4 v[196:197], off
	s_add_i32 m0, s58, 0xe000
	v_lshl_add_u64 v[196:197], s[72:73], 0, v[186:187]
	global_load_lds_dwordx4 v[196:197], off
	s_waitcnt vmcnt(8)
	s_waitcnt lgkmcnt(0)
	s_barrier
	s_waitcnt lgkmcnt(0)
	v_mfma_f32_16x16x32_bf16 v[2:5], v[130:133], v[162:165], v[2:5]
	v_mfma_f32_16x16x32_bf16 v[6:9], v[138:141], v[162:165], v[6:9]
	v_mfma_f32_16x16x32_bf16 v[14:17], v[130:133], v[170:173], v[14:17]
	v_mfma_f32_16x16x32_bf16 v[22:25], v[138:141], v[170:173], v[22:25]
	v_mfma_f32_16x16x32_bf16 v[30:33], v[130:133], v[178:181], v[30:33]
	v_mfma_f32_16x16x32_bf16 v[38:41], v[138:141], v[178:181], v[38:41]
	v_mfma_f32_16x16x32_bf16 v[46:49], v[130:133], v[188:191], v[46:49]
	v_mfma_f32_16x16x32_bf16 v[54:57], v[138:141], v[188:191], v[54:57]
	v_mfma_f32_16x16x32_bf16 v[2:5], v[134:137], v[166:169], v[2:5]
	v_mfma_f32_16x16x32_bf16 v[6:9], v[142:145], v[166:169], v[6:9]
	v_mfma_f32_16x16x32_bf16 v[14:17], v[134:137], v[174:177], v[14:17]
	v_mfma_f32_16x16x32_bf16 v[22:25], v[142:145], v[174:177], v[22:25]
	v_mfma_f32_16x16x32_bf16 v[30:33], v[134:137], v[182:185], v[30:33]
	v_mfma_f32_16x16x32_bf16 v[38:41], v[142:145], v[182:185], v[38:41]
	v_mfma_f32_16x16x32_bf16 v[46:49], v[134:137], v[192:195], v[46:49]
	v_mfma_f32_16x16x32_bf16 v[54:57], v[142:145], v[192:195], v[54:57]
	v_mfma_f32_16x16x32_bf16 v[10:13], v[146:149], v[162:165], v[10:13]
	v_mfma_f32_16x16x32_bf16 v[18:21], v[154:157], v[162:165], v[18:21]
	v_mfma_f32_16x16x32_bf16 v[26:29], v[146:149], v[170:173], v[26:29]
	v_mfma_f32_16x16x32_bf16 v[34:37], v[154:157], v[170:173], v[34:37]
	v_mfma_f32_16x16x32_bf16 v[42:45], v[146:149], v[178:181], v[42:45]
	v_mfma_f32_16x16x32_bf16 v[50:53], v[154:157], v[178:181], v[50:53]
	v_mfma_f32_16x16x32_bf16 v[58:61], v[146:149], v[188:191], v[58:61]
	v_mfma_f32_16x16x32_bf16 v[62:65], v[154:157], v[188:191], v[62:65]
	v_mfma_f32_16x16x32_bf16 v[10:13], v[150:153], v[166:169], v[10:13]
	v_mfma_f32_16x16x32_bf16 v[18:21], v[158:161], v[166:169], v[18:21]
	v_mfma_f32_16x16x32_bf16 v[26:29], v[150:153], v[174:177], v[26:29]
	v_mfma_f32_16x16x32_bf16 v[34:37], v[158:161], v[174:177], v[34:37]
	v_mfma_f32_16x16x32_bf16 v[42:45], v[150:153], v[182:185], v[42:45]
	v_mfma_f32_16x16x32_bf16 v[50:53], v[158:161], v[182:185], v[50:53]
	v_mfma_f32_16x16x32_bf16 v[58:61], v[150:153], v[192:195], v[58:61]
	v_mfma_f32_16x16x32_bf16 v[62:65], v[158:161], v[192:195], v[62:65]
	s_barrier
	s_mov_b64 s[72:73], s[52:53]
	ds_read_b128 v[162:165], v237 offset:16384
	ds_read_b128 v[166:169], v237 offset:17408
	ds_read_b128 v[170:173], v237 offset:18432
	ds_read_b128 v[174:177], v237 offset:19456
	ds_read_b128 v[178:181], v237 offset:20480
	ds_read_b128 v[182:185], v237 offset:21504
	ds_read_b128 v[188:191], v237 offset:22528
	ds_read_b128 v[192:195], v237 offset:23552
	s_add_i32 s74, s74, s57
	v_lshl_add_u64 v[196:197], s[72:73], 0, v[202:203]
	s_add_u32 s72, s72, 0xb0000
	s_mov_b32 m0, s74
	s_addc_u32 s73, s73, 0
	global_load_lds_dwordx4 v[196:197], off
	s_add_i32 m0, s74, 0x2000
	v_lshl_add_u64 v[196:197], s[72:73], 0, v[202:203]
	s_add_u32 s72, s52, 0x160000
	s_addc_u32 s73, s53, 0
	global_load_lds_dwordx4 v[196:197], off
	s_add_i32 s74, s75, s57
	v_lshl_add_u64 v[196:197], s[72:73], 0, v[202:203]
	s_add_u32 s72, s72, 0xb0000
	s_mov_b32 m0, s74
	s_addc_u32 s73, s73, 0
	global_load_lds_dwordx4 v[196:197], off
	s_add_i32 m0, s74, 0x2000
	v_lshl_add_u64 v[196:197], s[72:73], 0, v[202:203]
	s_mov_b64 s[72:73], s[54:55]
	global_load_lds_dwordx4 v[196:197], off
	s_mov_b32 m0, s58
	v_lshl_add_u64 v[196:197], s[72:73], 0, v[186:187]
	s_add_u32 s72, s72, 0xb0000
	s_addc_u32 s73, s73, 0
	global_load_lds_dwordx4 v[196:197], off
	s_mov_b32 m0, s59
	v_lshl_add_u64 v[196:197], s[72:73], 0, v[186:187]
	global_load_lds_dwordx4 v[196:197], off
	s_waitcnt vmcnt(8)
	s_waitcnt lgkmcnt(0)
	s_barrier
	s_waitcnt lgkmcnt(0)
	v_mfma_f32_16x16x32_bf16 v[66:69], v[130:133], v[162:165], v[66:69]
	v_mfma_f32_16x16x32_bf16 v[70:73], v[138:141], v[162:165], v[70:73]
	v_mfma_f32_16x16x32_bf16 v[74:77], v[130:133], v[170:173], v[74:77]
	v_mfma_f32_16x16x32_bf16 v[78:81], v[138:141], v[170:173], v[78:81]
	v_mfma_f32_16x16x32_bf16 v[86:89], v[130:133], v[178:181], v[86:89]
	v_mfma_f32_16x16x32_bf16 v[94:97], v[138:141], v[178:181], v[94:97]
	v_mfma_f32_16x16x32_bf16 v[102:105], v[130:133], v[188:191], v[102:105]
	v_mfma_f32_16x16x32_bf16 v[110:113], v[138:141], v[188:191], v[110:113]
	v_mfma_f32_16x16x32_bf16 v[66:69], v[134:137], v[166:169], v[66:69]
	v_mfma_f32_16x16x32_bf16 v[70:73], v[142:145], v[166:169], v[70:73]
	v_mfma_f32_16x16x32_bf16 v[74:77], v[134:137], v[174:177], v[74:77]
	v_mfma_f32_16x16x32_bf16 v[78:81], v[142:145], v[174:177], v[78:81]
	v_mfma_f32_16x16x32_bf16 v[86:89], v[134:137], v[182:185], v[86:89]
	v_mfma_f32_16x16x32_bf16 v[94:97], v[142:145], v[182:185], v[94:97]
	v_mfma_f32_16x16x32_bf16 v[102:105], v[134:137], v[192:195], v[102:105]
	v_mfma_f32_16x16x32_bf16 v[110:113], v[142:145], v[192:195], v[110:113]
	v_mfma_f32_16x16x32_bf16 v[82:85], v[146:149], v[162:165], v[82:85]
	v_mfma_f32_16x16x32_bf16 v[90:93], v[154:157], v[162:165], v[90:93]
	v_mfma_f32_16x16x32_bf16 v[98:101], v[146:149], v[170:173], v[98:101]
	v_mfma_f32_16x16x32_bf16 v[106:109], v[154:157], v[170:173], v[106:109]
	v_mfma_f32_16x16x32_bf16 v[114:117], v[146:149], v[178:181], v[114:117]
	v_mfma_f32_16x16x32_bf16 v[118:121], v[154:157], v[178:181], v[118:121]
	v_mfma_f32_16x16x32_bf16 v[122:125], v[146:149], v[188:191], v[122:125]
	v_mfma_f32_16x16x32_bf16 v[126:129], v[154:157], v[188:191], v[126:129]
	v_mfma_f32_16x16x32_bf16 v[82:85], v[150:153], v[166:169], v[82:85]
	v_mfma_f32_16x16x32_bf16 v[90:93], v[158:161], v[166:169], v[90:93]
	v_mfma_f32_16x16x32_bf16 v[98:101], v[150:153], v[174:177], v[98:101]
	v_mfma_f32_16x16x32_bf16 v[106:109], v[158:161], v[174:177], v[106:109]
	v_mfma_f32_16x16x32_bf16 v[114:117], v[150:153], v[182:185], v[114:117]
	v_mfma_f32_16x16x32_bf16 v[118:121], v[158:161], v[182:185], v[118:121]
	v_mfma_f32_16x16x32_bf16 v[122:125], v[150:153], v[192:195], v[122:125]
	v_mfma_f32_16x16x32_bf16 v[126:129], v[158:161], v[192:195], v[126:129]
	s_barrier
	s_add_i32 s72, 0, 0x18000
	s_add_i32 s73, 0, 0x1c000
	v_add_u32_e32 v142, s72, v207
	v_add_u32_e32 v158, s73, v207
	ds_read_b128 v[130:133], v142
	ds_read_b128 v[134:137], v142 offset:1024
	ds_read_b128 v[138:141], v142 offset:2048
	ds_read_b128 v[142:145], v142 offset:3072
	ds_read_b128 v[146:149], v158
	ds_read_b128 v[150:153], v158 offset:1024
	ds_read_b128 v[154:157], v158 offset:2048
	ds_read_b128 v[158:161], v158 offset:3072
	s_add_u32 s54, s54, 0x160000
	s_addc_u32 s55, s55, 0
	ds_read_b128 v[162:165], v237 offset:32768
	ds_read_b128 v[166:169], v237 offset:33792
	ds_read_b128 v[170:173], v237 offset:34816
	ds_read_b128 v[174:177], v237 offset:35840
	ds_read_b128 v[178:181], v237 offset:36864
	ds_read_b128 v[182:185], v237 offset:37888
	ds_read_b128 v[188:191], v237 offset:38912
	ds_read_b128 v[192:195], v237 offset:39936
	s_mov_b32 m0, s60
	v_lshl_add_u64 v[196:197], s[54:55], 0, v[186:187]
	s_add_u32 s54, s54, 0xb0000
	s_addc_u32 s55, s55, 0
	global_load_lds_dwordx4 v[196:197], off
	s_mov_b32 m0, s61
	v_lshl_add_u64 v[196:197], s[54:55], 0, v[186:187]
	global_load_lds_dwordx4 v[196:197], off
	s_waitcnt vmcnt(8)
	s_waitcnt lgkmcnt(0)
	s_barrier
	s_waitcnt lgkmcnt(0)
	v_mfma_f32_16x16x32_bf16 v[2:5], v[130:133], v[162:165], v[2:5]
	v_mfma_f32_16x16x32_bf16 v[6:9], v[138:141], v[162:165], v[6:9]
	v_mfma_f32_16x16x32_bf16 v[14:17], v[130:133], v[170:173], v[14:17]
	v_mfma_f32_16x16x32_bf16 v[22:25], v[138:141], v[170:173], v[22:25]
	v_mfma_f32_16x16x32_bf16 v[30:33], v[130:133], v[178:181], v[30:33]
	v_mfma_f32_16x16x32_bf16 v[38:41], v[138:141], v[178:181], v[38:41]
	v_mfma_f32_16x16x32_bf16 v[46:49], v[130:133], v[188:191], v[46:49]
	v_mfma_f32_16x16x32_bf16 v[54:57], v[138:141], v[188:191], v[54:57]
	v_mfma_f32_16x16x32_bf16 v[2:5], v[134:137], v[166:169], v[2:5]
	v_mfma_f32_16x16x32_bf16 v[6:9], v[142:145], v[166:169], v[6:9]
	v_mfma_f32_16x16x32_bf16 v[14:17], v[134:137], v[174:177], v[14:17]
	v_mfma_f32_16x16x32_bf16 v[22:25], v[142:145], v[174:177], v[22:25]
	v_mfma_f32_16x16x32_bf16 v[30:33], v[134:137], v[182:185], v[30:33]
	v_mfma_f32_16x16x32_bf16 v[38:41], v[142:145], v[182:185], v[38:41]
	v_mfma_f32_16x16x32_bf16 v[46:49], v[134:137], v[192:195], v[46:49]
	v_mfma_f32_16x16x32_bf16 v[54:57], v[142:145], v[192:195], v[54:57]
	v_mfma_f32_16x16x32_bf16 v[10:13], v[146:149], v[162:165], v[10:13]
	v_mfma_f32_16x16x32_bf16 v[18:21], v[154:157], v[162:165], v[18:21]
	v_mfma_f32_16x16x32_bf16 v[26:29], v[146:149], v[170:173], v[26:29]
	v_mfma_f32_16x16x32_bf16 v[34:37], v[154:157], v[170:173], v[34:37]
	v_mfma_f32_16x16x32_bf16 v[42:45], v[146:149], v[178:181], v[42:45]
	v_mfma_f32_16x16x32_bf16 v[50:53], v[154:157], v[178:181], v[50:53]
	v_mfma_f32_16x16x32_bf16 v[58:61], v[146:149], v[188:191], v[58:61]
	v_mfma_f32_16x16x32_bf16 v[62:65], v[154:157], v[188:191], v[62:65]
	v_mfma_f32_16x16x32_bf16 v[10:13], v[150:153], v[166:169], v[10:13]
	v_mfma_f32_16x16x32_bf16 v[18:21], v[158:161], v[166:169], v[18:21]
	v_mfma_f32_16x16x32_bf16 v[26:29], v[150:153], v[174:177], v[26:29]
	v_mfma_f32_16x16x32_bf16 v[34:37], v[158:161], v[174:177], v[34:37]
	v_mfma_f32_16x16x32_bf16 v[42:45], v[150:153], v[182:185], v[42:45]
	v_mfma_f32_16x16x32_bf16 v[50:53], v[158:161], v[182:185], v[50:53]
	v_mfma_f32_16x16x32_bf16 v[58:61], v[150:153], v[192:195], v[58:61]
	v_mfma_f32_16x16x32_bf16 v[62:65], v[158:161], v[192:195], v[62:65]
	s_barrier
	s_add_u32 s54, s52, 0x80
	s_addc_u32 s55, s53, 0
	ds_read_b128 v[162:165], v237 offset:49152
	ds_read_b128 v[166:169], v237 offset:50176
	ds_read_b128 v[170:173], v237 offset:51200
	ds_read_b128 v[174:177], v237 offset:52224
	ds_read_b128 v[178:181], v237 offset:53248
	ds_read_b128 v[182:185], v237 offset:54272
	ds_read_b128 v[188:191], v237 offset:55296
	ds_read_b128 v[192:195], v237 offset:56320
	s_add_i32 s72, s72, s57
	v_lshl_add_u64 v[196:197], s[54:55], 0, v[202:203]
	s_mov_b32 m0, s72
	s_add_u32 s54, s54, 0xb0000
	global_load_lds_dwordx4 v[196:197], off
	s_addc_u32 s55, s55, 0
	s_add_i32 m0, s72, 0x2000
	s_add_u32 s52, s52, 0x160080
	s_addc_u32 s53, s53, 0
	v_lshl_add_u64 v[196:197], s[54:55], 0, v[202:203]
	global_load_lds_dwordx4 v[196:197], off
	s_add_i32 s54, s73, s57
	v_lshl_add_u64 v[196:197], s[52:53], 0, v[202:203]
	s_add_u32 s52, s52, 0xb0000
	s_mov_b32 m0, s54
	s_addc_u32 s53, s53, 0
	global_load_lds_dwordx4 v[196:197], off
	s_add_i32 m0, s54, 0x2000
	v_lshl_add_u64 v[196:197], s[52:53], 0, v[202:203]
	global_load_lds_dwordx4 v[196:197], off
	s_mov_b32 m0, s62
	v_lshl_add_u64 v[196:197], s[46:47], 0, v[186:187]
	s_add_u32 s46, s46, 0xb0000
	s_addc_u32 s47, s47, 0
	global_load_lds_dwordx4 v[196:197], off
	s_mov_b32 m0, s63
	v_lshl_add_u64 v[196:197], s[46:47], 0, v[186:187]
	global_load_lds_dwordx4 v[196:197], off
	s_waitcnt vmcnt(8)
	s_waitcnt lgkmcnt(0)
	s_barrier
	s_waitcnt lgkmcnt(0)
	v_mfma_f32_16x16x32_bf16 v[66:69], v[130:133], v[162:165], v[66:69]
	v_mfma_f32_16x16x32_bf16 v[70:73], v[138:141], v[162:165], v[70:73]
	v_mfma_f32_16x16x32_bf16 v[74:77], v[130:133], v[170:173], v[74:77]
	v_mfma_f32_16x16x32_bf16 v[78:81], v[138:141], v[170:173], v[78:81]
	v_mfma_f32_16x16x32_bf16 v[86:89], v[130:133], v[178:181], v[86:89]
	v_mfma_f32_16x16x32_bf16 v[94:97], v[138:141], v[178:181], v[94:97]
	v_mfma_f32_16x16x32_bf16 v[102:105], v[130:133], v[188:191], v[102:105]
	v_mfma_f32_16x16x32_bf16 v[110:113], v[138:141], v[188:191], v[110:113]
	v_mfma_f32_16x16x32_bf16 v[66:69], v[134:137], v[166:169], v[66:69]
	v_mfma_f32_16x16x32_bf16 v[70:73], v[142:145], v[166:169], v[70:73]
	v_mfma_f32_16x16x32_bf16 v[74:77], v[134:137], v[174:177], v[74:77]
	v_mfma_f32_16x16x32_bf16 v[78:81], v[142:145], v[174:177], v[78:81]
	v_mfma_f32_16x16x32_bf16 v[86:89], v[134:137], v[182:185], v[86:89]
	v_mfma_f32_16x16x32_bf16 v[94:97], v[142:145], v[182:185], v[94:97]
	v_mfma_f32_16x16x32_bf16 v[102:105], v[134:137], v[192:195], v[102:105]
	v_mfma_f32_16x16x32_bf16 v[110:113], v[142:145], v[192:195], v[110:113]
	v_mfma_f32_16x16x32_bf16 v[82:85], v[146:149], v[162:165], v[82:85]
	v_mfma_f32_16x16x32_bf16 v[90:93], v[154:157], v[162:165], v[90:93]
	v_mfma_f32_16x16x32_bf16 v[98:101], v[146:149], v[170:173], v[98:101]
	v_mfma_f32_16x16x32_bf16 v[106:109], v[154:157], v[170:173], v[106:109]
	v_mfma_f32_16x16x32_bf16 v[114:117], v[146:149], v[178:181], v[114:117]
	v_mfma_f32_16x16x32_bf16 v[118:121], v[154:157], v[178:181], v[118:121]
	v_mfma_f32_16x16x32_bf16 v[122:125], v[146:149], v[188:191], v[122:125]
	v_mfma_f32_16x16x32_bf16 v[126:129], v[154:157], v[188:191], v[126:129]
	v_mfma_f32_16x16x32_bf16 v[82:85], v[150:153], v[166:169], v[82:85]
	v_mfma_f32_16x16x32_bf16 v[90:93], v[158:161], v[166:169], v[90:93]
	v_mfma_f32_16x16x32_bf16 v[98:101], v[150:153], v[174:177], v[98:101]
	v_mfma_f32_16x16x32_bf16 v[106:109], v[158:161], v[174:177], v[106:109]
	v_mfma_f32_16x16x32_bf16 v[114:117], v[150:153], v[182:185], v[114:117]
	v_mfma_f32_16x16x32_bf16 v[118:121], v[158:161], v[182:185], v[118:121]
	v_mfma_f32_16x16x32_bf16 v[122:125], v[150:153], v[192:195], v[122:125]
	v_mfma_f32_16x16x32_bf16 v[126:129], v[158:161], v[192:195], v[126:129]
	s_barrier
	s_add_i32 s71, s71, 2
	s_add_u32 s9, s9, 0x100
	s_addc_u32 s27, s27, 0
	s_add_u32 s28, s28, 0x100
	s_addc_u32 s29, s29, 0
	s_add_u32 s44, s44, 0x100
	s_addc_u32 s45, s45, 0
	s_cmpk_gt_u32 s71, 0x55
	s_cbranch_scc0 .LBB0_1286
	s_and_b64 vcc, exec, s[18:19]
	s_cbranch_vccz .LBB0_1289
	s_barrier
